# dependency counters with deferred signalling: tile counter bump sent at the next epilogue start, last one at norm entry (no per-tile store drain)
# baseline (speedup 1.0000x reference)
; #define LAS __attribute__((address_space(3)))
; __global__ void __launch_bounds__(256, 2) mega(Params p, int ph_lo, int ph_hi) {
;   __shared__ __attribute__((aligned(16))) char lds[65536 + 16];
;   cg::grid_group grid = cg::this_grid();
;   volatile LAS unsigned* st = (volatile LAS unsigned*)(lds + 65536);
;   if (threadIdx.x == 0) { st[0] = 0u; st[1] = 0u; }
;   __syncthreads();
;   XcdBarrier xb = xcd_barrier_post(p.BAR, st);
_Z4mega6Paramsii:
	v_writelane_b32 v250, 0, 42
	s_load_dwordx16 s[56:71], s[0:1], 0x100
	s_load_dwordx2 s[52:53], s[0:1], 0x1e8
	s_add_u32 s4, s0, 0x1e8
	s_addc_u32 s5, s1, 0
	v_and_b32_e32 v138, 0x3ff, v0
	v_writelane_b32 v251, s4, 0
	s_nop 1
	v_writelane_b32 v251, s5, 1
	v_cmp_eq_u32_e64 s[4:5], 0, v138
	s_mov_b64 s[6:7], exec
	s_nop 0
	v_writelane_b32 v251, s4, 2
	s_nop 1
	v_writelane_b32 v251, s5, 3
	s_and_b64 s[4:5], s[6:7], s[4:5]
	s_mov_b64 exec, s[4:5]
	s_cbranch_execz .LBB0_2
	v_mov_b32_e32 v1, 0
	v_mov_b32_e32 v2, 0x10000
	ds_write_b32 v2, v1
	v_mov_b32_e32 v2, 0x10004
	ds_write_b32 v2, v1

; template <class Epi>
; DI void gemm_tile(const bf16_t* __restrict__ A, int lda, const bf16_t* __restrict__ Bt, int ldb, int K, int row0, int col0, char* lds, const Epi& epi) {
;     ...
;   for (int kt = 0; kt < KT; ++kt) {
;     asm volatile("s_waitcnt vmcnt(0)" ::: "memory");
;     __syncthreads();
;     const char* sa = lds + (kt & 1) * 32768 + (wr * 64 + fr) * 128;
;     const char* sb = lds + (kt & 1) * 32768 + 16384 + (wc * 64 + fr) * 128;
; #pragma unroll
;     for (int kk = 0; kk < 2; ++kk) {
;       if (kt + 1 < KT) { if (kk == 0) stage_a(kt + 1, (kt + 1) & 1); else stage_b(kt + 1, (kt + 1) & 1); }
;       bf16x8 a[4], b[4];
;       const int co = ((kk * 4 + fq) ^ swz) * 16;
; #pragma unroll
;       for (int m = 0; m < 4; ++m) a[m] = *(const bf16x8*)(sa + m * 2048 + co);
; #pragma unroll
;       for (int n = 0; n < 4; ++n) b[n] = *(const bf16x8*)(sb + n * 2048 + co);
; #pragma unroll
;       for (int m = 0; m < 4; ++m)
; #pragma unroll
;         for (int n = 0; n < 4; ++n) acc[m][n] = __builtin_amdgcn_mfma_f32_16x16x32_bf16(b[n], a[m], acc[m][n], 0, 0, 0);
;     }
;   }
.LBB0_84:
	s_add_i32 s20, s28, 0xffff8000
	s_and_b32 s29, s28, 0x8000
	s_and_b32 s20, s20, 0x8000
	v_add_u32_e32 v102, s29, v90
	v_add_u32_e32 v110, s20, v91
	v_or_b32_e32 v136, s20, v93
	v_add_u32_e32 v103, 0x1000, v102
	v_readfirstlane_b32 s20, v102
	v_lshl_add_u64 v[94:95], v[74:75], 0, s[0:1]
	v_add_u32_e32 v104, 0x2000, v102
	s_mov_b32 m0, s20
	v_readfirstlane_b32 s20, v103
	s_waitcnt vmcnt(0)
	s_waitcnt vmcnt(0) lgkmcnt(0)
	s_barrier
	v_lshl_add_u64 v[96:97], v[76:77], 0, s[0:1]
	v_add_u32_e32 v105, 0x3000, v102
	global_load_lds_dwordx4 v[94:95], off
	s_mov_b32 m0, s20
	v_readfirstlane_b32 s20, v104
	v_add_u32_e32 v137, 0x4000, v102
	v_lshl_add_u64 v[98:99], v[78:79], 0, s[0:1]
	global_load_lds_dwordx4 v[96:97], off
	s_mov_b32 m0, s20
	v_readfirstlane_b32 s20, v105
	v_add_u32_e32 v159, 0x5000, v102
	v_lshl_add_u64 v[100:101], v[80:81], 0, s[0:1]
	global_load_lds_dwordx4 v[98:99], off
	s_mov_b32 m0, s20
	v_readfirstlane_b32 s20, v137
	v_lshl_add_u64 v[132:133], v[66:67], 0, s[0:1]
	v_add_u32_e32 v160, 0x6000, v102
	global_load_lds_dwordx4 v[100:101], off
	v_add_u32_e32 v106, v110, v92
	v_add_u32_e32 v128, v136, v92
	s_mov_b32 m0, s20
	v_readfirstlane_b32 s20, v159
	v_lshl_add_u64 v[134:135], v[68:69], 0, s[0:1]
	v_add_u32_e32 v161, 0x7000, v102
	ds_read_b128 v[94:97], v106
	ds_read_b128 v[98:101], v106 offset:2048
	ds_read_b128 v[102:105], v106 offset:4096
	ds_read_b128 v[106:109], v106 offset:6144
	ds_read_b128 v[116:119], v128 offset:16384
	ds_read_b128 v[120:123], v128 offset:18432
	ds_read_b128 v[124:127], v128 offset:20480
	ds_read_b128 v[128:131], v128 offset:22528
	global_load_lds_dwordx4 v[132:133], off
	s_mov_b32 m0, s20
	v_readfirstlane_b32 s20, v160
	v_lshl_add_u64 v[84:85], v[70:71], 0, s[0:1]
	global_load_lds_dwordx4 v[134:135], off
	s_mov_b32 m0, s20
	v_readfirstlane_b32 s20, v161
	v_lshl_add_u64 v[82:83], v[72:73], 0, s[0:1]
	global_load_lds_dwordx4 v[84:85], off
	s_mov_b32 m0, s20
	s_waitcnt lgkmcnt(0)
	v_mfma_f32_16x16x32_bf16 v[30:33], v[116:119], v[102:105], v[30:33]
	global_load_lds_dwordx4 v[82:83], off
	s_add_u32 s0, s0, 0x80
	v_mfma_f32_16x16x32_bf16 v[26:29], v[120:123], v[102:105], v[26:29]
	s_addc_u32 s1, s1, 0
	s_add_i32 s28, s28, 0x8000
	s_cmpk_eq_i32 s0, 0x1580
	v_mfma_f32_16x16x32_bf16 v[22:25], v[124:127], v[102:105], v[22:25]
	v_mfma_f32_16x16x32_bf16 v[18:21], v[128:131], v[102:105], v[18:21]
	v_add_u32_e32 v102, v110, v89
	v_add_u32_e32 v110, v136, v89
	v_mfma_f32_16x16x32_bf16 v[62:65], v[116:119], v[94:97], v[62:65]
	v_mfma_f32_16x16x32_bf16 v[58:61], v[120:123], v[94:97], v[58:61]
	v_mfma_f32_16x16x32_bf16 v[54:57], v[124:127], v[94:97], v[54:57]
	v_mfma_f32_16x16x32_bf16 v[50:53], v[128:131], v[94:97], v[50:53]
	v_mfma_f32_16x16x32_bf16 v[46:49], v[116:119], v[98:101], v[46:49]
	v_mfma_f32_16x16x32_bf16 v[42:45], v[120:123], v[98:101], v[42:45]
	v_mfma_f32_16x16x32_bf16 v[38:41], v[124:127], v[98:101], v[38:41]
	v_mfma_f32_16x16x32_bf16 v[34:37], v[128:131], v[98:101], v[34:37]
	ds_read_b128 v[82:85], v102
	ds_read_b128 v[94:97], v102 offset:2048
	ds_read_b128 v[98:101], v102 offset:4096
	ds_read_b128 v[102:105], v102 offset:6144
	v_mfma_f32_16x16x32_bf16 v[14:17], v[116:119], v[106:109], v[14:17]
	v_mfma_f32_16x16x32_bf16 v[10:13], v[120:123], v[106:109], v[10:13]
	v_mfma_f32_16x16x32_bf16 v[6:9], v[124:127], v[106:109], v[6:9]
	v_mfma_f32_16x16x32_bf16 v[2:5], v[128:131], v[106:109], v[2:5]
	ds_read_b128 v[106:109], v110 offset:16384
	ds_read_b128 v[116:119], v110 offset:18432
	ds_read_b128 v[120:123], v110 offset:20480
	ds_read_b128 v[124:127], v110 offset:22528
	s_waitcnt lgkmcnt(0)
	v_mfma_f32_16x16x32_bf16 v[62:65], v[106:109], v[82:85], v[62:65]
	v_mfma_f32_16x16x32_bf16 v[58:61], v[116:119], v[82:85], v[58:61]
	v_mfma_f32_16x16x32_bf16 v[54:57], v[120:123], v[82:85], v[54:57]
	v_mfma_f32_16x16x32_bf16 v[50:53], v[124:127], v[82:85], v[50:53]
	v_mfma_f32_16x16x32_bf16 v[46:49], v[106:109], v[94:97], v[46:49]
	v_mfma_f32_16x16x32_bf16 v[42:45], v[116:119], v[94:97], v[42:45]
	v_mfma_f32_16x16x32_bf16 v[38:41], v[120:123], v[94:97], v[38:41]
	v_mfma_f32_16x16x32_bf16 v[34:37], v[124:127], v[94:97], v[34:37]
	v_mfma_f32_16x16x32_bf16 v[30:33], v[106:109], v[98:101], v[30:33]
	v_mfma_f32_16x16x32_bf16 v[26:29], v[116:119], v[98:101], v[26:29]
	v_mfma_f32_16x16x32_bf16 v[22:25], v[120:123], v[98:101], v[22:25]
	v_mfma_f32_16x16x32_bf16 v[18:21], v[124:127], v[98:101], v[18:21]
	v_mfma_f32_16x16x32_bf16 v[14:17], v[106:109], v[102:105], v[14:17]
	v_mfma_f32_16x16x32_bf16 v[10:13], v[116:119], v[102:105], v[10:13]
	v_mfma_f32_16x16x32_bf16 v[6:9], v[120:123], v[102:105], v[6:9]
	v_mfma_f32_16x16x32_bf16 v[2:5], v[124:127], v[102:105], v[2:5]
	s_cbranch_scc0 .LBB0_84
	v_add_u32_e32 v90, s29, v93
	v_add_u32_e32 v91, s29, v91
	v_add_u32_e32 v82, v90, v92
	v_add_u32_e32 v92, v91, v92
	s_waitcnt vmcnt(0)
	s_waitcnt vmcnt(0)
	s_barrier
; template <class Epi>
; DI void gemm_tile(const bf16_t* __restrict__ A, int lda, const bf16_t* __restrict__ Bt, int ldb, int K, int row0, int col0, char* lds, const Epi& epi) {
;     ...
;       for (int m = 0; m < 4; ++m) a[m] = *(const bf16x8*)(sa + m * 2048 + co);
; #pragma unroll
;       for (int n = 0; n < 4; ++n) b[n] = *(const bf16x8*)(sb + n * 2048 + co);
; #pragma unroll
;       for (int m = 0; m < 4; ++m)
; #pragma unroll
;         for (int n = 0; n < 4; ++n) acc[m][n] = __builtin_amdgcn_mfma_f32_16x16x32_bf16(b[n], a[m], acc[m][n], 0, 0, 0);
;   DI void operator()(const f32x4 (&acc)[4][4], int r0, int c0, int fr, int fq) const {
; #pragma unroll
;     for (int m = 0; m < 4; ++m) {
;       const int row = r0 + m * 16 + fr; const int b = row / TB, s = row % TB;
;       const float* src = xsrc_row(*p, from_inputs, b, s);
;       float* dst = xdst_row(*p, b, s);
;       const float* gate = p->MOD + (size_t)(l * 9 + (s < NCTX ? 8 : b)) * 6144 + gate_off;
; #pragma unroll
;       for (int n = 0; n < 4; ++n) {
;         const int col = c0 + n * 16 + fq * 4;
;         f32x4 g = *(const f32x4*)(gate + col), xv = *(const f32x4*)(src + col);
	ds_read_b128 v[66:69], v82 offset:16384
	ds_read_b128 v[74:77], v82 offset:18432
	ds_read_b128 v[70:73], v92
	ds_read_b128 v[78:81], v82 offset:20480
	ds_read_b128 v[82:85], v82 offset:22528
	s_waitcnt lgkmcnt(2)
	v_mfma_f32_16x16x32_bf16 v[62:65], v[66:69], v[70:73], v[62:65]
	v_mfma_f32_16x16x32_bf16 v[58:61], v[74:77], v[70:73], v[58:61]
	s_waitcnt lgkmcnt(1)
	v_mfma_f32_16x16x32_bf16 v[54:57], v[78:81], v[70:73], v[54:57]
	s_waitcnt lgkmcnt(0)
	v_mfma_f32_16x16x32_bf16 v[50:53], v[82:85], v[70:73], v[50:53]
	ds_read_b128 v[70:73], v92 offset:2048
	s_waitcnt lgkmcnt(0)
	v_mfma_f32_16x16x32_bf16 v[46:49], v[66:69], v[70:73], v[46:49]
	v_mfma_f32_16x16x32_bf16 v[42:45], v[74:77], v[70:73], v[42:45]
	v_mfma_f32_16x16x32_bf16 v[38:41], v[78:81], v[70:73], v[38:41]
	v_mfma_f32_16x16x32_bf16 v[34:37], v[82:85], v[70:73], v[34:37]
	ds_read_b128 v[70:73], v92 offset:4096
	s_waitcnt lgkmcnt(0)
	v_mfma_f32_16x16x32_bf16 v[30:33], v[66:69], v[70:73], v[30:33]
	v_mfma_f32_16x16x32_bf16 v[26:29], v[74:77], v[70:73], v[26:29]
	v_mfma_f32_16x16x32_bf16 v[22:25], v[78:81], v[70:73], v[22:25]
	v_mfma_f32_16x16x32_bf16 v[18:21], v[82:85], v[70:73], v[18:21]
	ds_read_b128 v[70:73], v92 offset:6144
	s_waitcnt lgkmcnt(0)
	v_mfma_f32_16x16x32_bf16 v[10:13], v[74:77], v[70:73], v[10:13]
	v_add_u32_e32 v74, v90, v89
	v_add_u32_e32 v75, v91, v89
	ds_read_b128 v[90:93], v74 offset:22528
	v_mfma_f32_16x16x32_bf16 v[14:17], v[66:69], v[70:73], v[14:17]
	ds_read_b128 v[66:69], v74 offset:16384
	ds_read_b128 v[94:97], v75 offset:6144
	v_mfma_f32_16x16x32_bf16 v[6:9], v[78:81], v[70:73], v[6:9]
	ds_read_b128 v[76:79], v74 offset:18432
	v_mfma_f32_16x16x32_bf16 v[2:5], v[82:85], v[70:73], v[2:5]
	ds_read_b128 v[80:83], v74 offset:20480
	ds_read_b128 v[70:73], v75
	s_waitcnt lgkmcnt(0)
	v_mfma_f32_16x16x32_bf16 v[62:65], v[66:69], v[70:73], v[62:65]
	v_mfma_f32_16x16x32_bf16 v[58:61], v[76:79], v[70:73], v[58:61]
	v_mfma_f32_16x16x32_bf16 v[54:57], v[80:83], v[70:73], v[54:57]
	v_mfma_f32_16x16x32_bf16 v[50:53], v[90:93], v[70:73], v[50:53]
	ds_read_b128 v[70:73], v75 offset:2048
	s_waitcnt lgkmcnt(0)
	v_mfma_f32_16x16x32_bf16 v[46:49], v[66:69], v[70:73], v[46:49]
	v_mfma_f32_16x16x32_bf16 v[42:45], v[76:79], v[70:73], v[42:45]
	v_mfma_f32_16x16x32_bf16 v[38:41], v[80:83], v[70:73], v[38:41]
	v_mfma_f32_16x16x32_bf16 v[34:37], v[90:93], v[70:73], v[34:37]
	ds_read_b128 v[70:73], v75 offset:4096
	s_waitcnt lgkmcnt(0)
	v_mfma_f32_16x16x32_bf16 v[30:33], v[66:69], v[70:73], v[30:33]
	v_mfma_f32_16x16x32_bf16 v[26:29], v[76:79], v[70:73], v[26:29]
	v_mfma_f32_16x16x32_bf16 v[22:25], v[80:83], v[70:73], v[22:25]
	v_mfma_f32_16x16x32_bf16 v[18:21], v[90:93], v[70:73], v[18:21]
	v_or_b32_e32 v70, s3, v87
	v_lshl_add_u32 v74, v88, 6, v70
	v_mfma_f32_16x16x32_bf16 v[14:17], v[66:69], v[94:97], v[14:17]
	v_mul_hi_i32 v66, v74, s47
	v_lshrrev_b32_e32 v67, 31, v66
	v_ashrrev_i32_e32 v66, 9, v66
	v_mfma_f32_16x16x32_bf16 v[10:13], v[76:79], v[94:97], v[10:13]
	v_add_u32_e32 v75, v66, v67
	v_mul_i32_i24_e32 v66, 0x900, v75
	v_sub_u32_e32 v71, v74, v66
	v_mfma_f32_16x16x32_bf16 v[6:9], v[80:83], v[94:97], v[6:9]
	v_lshlrev_b32_e32 v67, 11, v75
	v_cmp_lt_i32_e32 vcc, s33, v71
	v_mov_b64_e32 v[68:69], s[64:65]
	v_mfma_f32_16x16x32_bf16 v[2:5], v[90:93], v[94:97], v[2:5]
	v_readlane_b32 s0, v250, 42
	s_nop 1
	s_cmp_eq_u32 s0, 0
	s_cbranch_scc1 .Ldep_nop_k9
	v_mov_b32_e32 v88, s0
	v_mov_b32_e32 v89, 1
	v_cmp_eq_u32_e32 vcc, 0, v138
	s_and_saveexec_b64 s[0:1], vcc
	global_atomic_add v88, v89, s[70:71]
	s_or_b64 exec, exec, s[0:1]
.Ldep_nop_k9:
	v_lshlrev_b32_e32 v1, 6, v1
	v_lshlrev_b32_e32 v67, 2, v86
	v_or3_b32 v80, v1, v67, s2
	v_lshlrev_b32_e32 v66, 2, v80
	v_mov_b32_e32 v67, 0
	v_mov_b32_e32 v100, s64
	v_mov_b32_e32 v101, s65
	v_mov_b32_e32 v102, s56
	v_mov_b32_e32 v103, s57
	s_add_u32 s0, s58, 0x5000
	s_addc_u32 s1, s59, 0
	v_mov_b32_e32 v108, s0
	v_mov_b32_e32 v109, s1
	v_mov_b32_e32 v110, 8
	v_mov_b32_e32 v88, v74
	v_mul_hi_i32 v89, v88, s47
	v_lshrrev_b32_e32 v90, 31, v89
	v_ashrrev_i32_e32 v89, 9, v89
	v_add_u32_e32 v91, v89, v90
	v_mul_i32_i24_e32 v89, 0x900, v91
	v_sub_u32_e32 v92, v88, v89
	v_cmp_lt_i32_e32 vcc, s33, v92
	v_lshlrev_b32_e32 v89, 11, v91
	v_add3_u32 v89, v92, v89, s75
	v_lshl_add_u32 v90, v91, 8, v92
	v_cndmask_b32_e32 v94, v90, v89, vcc
	v_ashrrev_i32_e32 v95, 31, v94
	v_lshlrev_b64 v[96:97], 12, v[94:95]
	v_lshl_add_u64 v[96:97], v[96:97], 0, v[66:67]
	v_cndmask_b32_e32 v98, v100, v102, vcc
	v_cndmask_b32_e32 v99, v101, v103, vcc
	v_lshl_add_u64 v[224:225], v[98:99], 0, v[96:97]
	v_cndmask_b32_e32 v93, v110, v91, vcc
	v_add_u32_e32 v93, s82, v93
	v_mad_i64_i32 v[240:241], s[0:1], v93, s24, v[108:109]
	s_nop 0
	v_lshl_add_u64 v[240:241], v[240:241], 0, v[66:67]
	global_load_dwordx4 v[116:119], v[240:241], off
	global_load_dwordx4 v[120:123], v[240:241], off offset:64
	global_load_dwordx4 v[124:127], v[240:241], off offset:128
	global_load_dwordx4 v[128:131], v[240:241], off offset:192
	global_load_dwordx4 v[160:163], v[224:225], off
	global_load_dwordx4 v[164:167], v[224:225], off offset:64
	global_load_dwordx4 v[168:171], v[224:225], off offset:128
	global_load_dwordx4 v[172:175], v[224:225], off offset:192
	v_or_b32_e32 v88, 16, v74
	v_mul_hi_i32 v89, v88, s47
	v_lshrrev_b32_e32 v90, 31, v89
	v_ashrrev_i32_e32 v89, 9, v89
	v_add_u32_e32 v91, v89, v90
	v_mul_i32_i24_e32 v89, 0x900, v91
	v_sub_u32_e32 v92, v88, v89
	v_cmp_lt_i32_e32 vcc, s33, v92
	v_lshlrev_b32_e32 v89, 11, v91
	v_add3_u32 v89, v92, v89, s75
	v_lshl_add_u32 v90, v91, 8, v92
;   DI void operator()(const f32x4 (&acc)[4][4], int r0, int c0, int fr, int fq) const {
; #pragma unroll
;     for (int m = 0; m < 4; ++m) {
;       const int row = r0 + m * 16 + fr; const int b = row / TB, s = row % TB;
;       const float* src = xsrc_row(*p, from_inputs, b, s);
;       float* dst = xdst_row(*p, b, s);
;       const float* gate = p->MOD + (size_t)(l * 9 + (s < NCTX ? 8 : b)) * 6144 + gate_off;
; #pragma unroll
;       for (int n = 0; n < 4; ++n) {
;         const int col = c0 + n * 16 + fq * 4;
;         f32x4 g = *(const f32x4*)(gate + col), xv = *(const f32x4*)(src + col);
;         *(f32x4*)(dst + col) = xv + g * acc[m][n];
;       }
;     }
	v_cndmask_b32_e32 v94, v90, v89, vcc
	v_ashrrev_i32_e32 v95, 31, v94
	v_lshlrev_b64 v[96:97], 12, v[94:95]
	v_lshl_add_u64 v[96:97], v[96:97], 0, v[66:67]
	v_cndmask_b32_e32 v98, v100, v102, vcc
	v_cndmask_b32_e32 v99, v101, v103, vcc
	v_lshl_add_u64 v[226:227], v[98:99], 0, v[96:97]
	global_load_dwordx4 v[176:179], v[226:227], off
	global_load_dwordx4 v[180:183], v[226:227], off offset:64
	global_load_dwordx4 v[184:187], v[226:227], off offset:128
	global_load_dwordx4 v[188:191], v[226:227], off offset:192
	v_or_b32_e32 v88, 32, v74
	v_mul_hi_i32 v89, v88, s47
	v_lshrrev_b32_e32 v90, 31, v89
	v_ashrrev_i32_e32 v89, 9, v89
	v_add_u32_e32 v91, v89, v90
	v_mul_i32_i24_e32 v89, 0x900, v91
	v_sub_u32_e32 v92, v88, v89
	v_cmp_lt_i32_e32 vcc, s33, v92
	v_lshlrev_b32_e32 v89, 11, v91
	v_add3_u32 v89, v92, v89, s75
	v_lshl_add_u32 v90, v91, 8, v92
	v_cndmask_b32_e32 v94, v90, v89, vcc
	v_ashrrev_i32_e32 v95, 31, v94
	v_lshlrev_b64 v[96:97], 12, v[94:95]
	v_lshl_add_u64 v[96:97], v[96:97], 0, v[66:67]
	v_cndmask_b32_e32 v98, v100, v102, vcc
	v_cndmask_b32_e32 v99, v101, v103, vcc
	v_lshl_add_u64 v[228:229], v[98:99], 0, v[96:97]
	global_load_dwordx4 v[192:195], v[228:229], off
	global_load_dwordx4 v[196:199], v[228:229], off offset:64
	global_load_dwordx4 v[200:203], v[228:229], off offset:128
	global_load_dwordx4 v[204:207], v[228:229], off offset:192
	v_or_b32_e32 v88, 48, v74
	v_mul_hi_i32 v89, v88, s47
	v_lshrrev_b32_e32 v90, 31, v89
	v_ashrrev_i32_e32 v89, 9, v89
	v_add_u32_e32 v91, v89, v90
	v_mul_i32_i24_e32 v89, 0x900, v91
	v_sub_u32_e32 v92, v88, v89
	v_cmp_lt_i32_e32 vcc, s33, v92
	v_lshlrev_b32_e32 v89, 11, v91
	v_add3_u32 v89, v92, v89, s75
	v_lshl_add_u32 v90, v91, 8, v92
	v_cndmask_b32_e32 v94, v90, v89, vcc
	v_ashrrev_i32_e32 v95, 31, v94
	v_lshlrev_b64 v[96:97], 12, v[94:95]
	v_lshl_add_u64 v[96:97], v[96:97], 0, v[66:67]
	v_cndmask_b32_e32 v98, v100, v102, vcc
	v_cndmask_b32_e32 v99, v101, v103, vcc
	v_lshl_add_u64 v[230:231], v[98:99], 0, v[96:97]
	global_load_dwordx4 v[208:211], v[230:231], off
	global_load_dwordx4 v[212:215], v[230:231], off offset:64
	global_load_dwordx4 v[216:219], v[230:231], off offset:128
	global_load_dwordx4 v[220:223], v[230:231], off offset:192
	s_waitcnt vmcnt(15)
	v_pk_fma_f32 v[64:65], v[64:65], v[118:119], v[162:163]
	v_pk_fma_f32 v[62:63], v[62:63], v[116:117], v[160:161]
	global_store_dwordx4 v[224:225], v[62:65], off sc0 sc1
	s_waitcnt vmcnt(15)
	v_pk_fma_f32 v[60:61], v[60:61], v[122:123], v[166:167]
	v_pk_fma_f32 v[58:59], v[58:59], v[120:121], v[164:165]
	global_store_dwordx4 v[224:225], v[58:61], off offset:64 sc0 sc1
	s_waitcnt vmcnt(15)
	v_pk_fma_f32 v[56:57], v[56:57], v[126:127], v[170:171]
	v_pk_fma_f32 v[54:55], v[54:55], v[124:125], v[168:169]
	global_store_dwordx4 v[224:225], v[54:57], off offset:128 sc0 sc1
	s_waitcnt vmcnt(15)
	v_pk_fma_f32 v[52:53], v[52:53], v[130:131], v[174:175]
	v_pk_fma_f32 v[50:51], v[50:51], v[128:129], v[172:173]
	global_store_dwordx4 v[224:225], v[50:53], off offset:192 sc0 sc1
	s_waitcnt vmcnt(15)
	v_pk_fma_f32 v[48:49], v[48:49], v[118:119], v[178:179]
	v_pk_fma_f32 v[46:47], v[46:47], v[116:117], v[176:177]
	global_store_dwordx4 v[226:227], v[46:49], off sc0 sc1
	s_waitcnt vmcnt(15)
	v_pk_fma_f32 v[44:45], v[44:45], v[122:123], v[182:183]
	v_pk_fma_f32 v[42:43], v[42:43], v[120:121], v[180:181]
	global_store_dwordx4 v[226:227], v[42:45], off offset:64 sc0 sc1
	s_waitcnt vmcnt(15)
	v_pk_fma_f32 v[40:41], v[40:41], v[126:127], v[186:187]
	v_pk_fma_f32 v[38:39], v[38:39], v[124:125], v[184:185]
	global_store_dwordx4 v[226:227], v[38:41], off offset:128 sc0 sc1
	s_waitcnt vmcnt(15)
	v_pk_fma_f32 v[36:37], v[36:37], v[130:131], v[190:191]
	v_pk_fma_f32 v[34:35], v[34:35], v[128:129], v[188:189]
	global_store_dwordx4 v[226:227], v[34:37], off offset:192 sc0 sc1
	s_waitcnt vmcnt(15)
	v_pk_fma_f32 v[32:33], v[32:33], v[118:119], v[194:195]
	v_pk_fma_f32 v[30:31], v[30:31], v[116:117], v[192:193]
	global_store_dwordx4 v[228:229], v[30:33], off sc0 sc1
	s_waitcnt vmcnt(15)
	v_pk_fma_f32 v[28:29], v[28:29], v[122:123], v[198:199]
	v_pk_fma_f32 v[26:27], v[26:27], v[120:121], v[196:197]
	global_store_dwordx4 v[228:229], v[26:29], off offset:64 sc0 sc1
	s_waitcnt vmcnt(15)
	v_pk_fma_f32 v[24:25], v[24:25], v[126:127], v[202:203]
	v_pk_fma_f32 v[22:23], v[22:23], v[124:125], v[200:201]
	global_store_dwordx4 v[228:229], v[22:25], off offset:128 sc0 sc1
	s_waitcnt vmcnt(15)
	v_pk_fma_f32 v[20:21], v[20:21], v[130:131], v[206:207]
	v_pk_fma_f32 v[18:19], v[18:19], v[128:129], v[204:205]
	global_store_dwordx4 v[228:229], v[18:21], off offset:192 sc0 sc1
	s_waitcnt vmcnt(15)
	v_pk_fma_f32 v[16:17], v[16:17], v[118:119], v[210:211]
	v_pk_fma_f32 v[14:15], v[14:15], v[116:117], v[208:209]
	global_store_dwordx4 v[230:231], v[14:17], off sc0 sc1
	s_waitcnt vmcnt(15)
	v_pk_fma_f32 v[12:13], v[12:13], v[122:123], v[214:215]
	v_pk_fma_f32 v[10:11], v[10:11], v[120:121], v[212:213]
	global_store_dwordx4 v[230:231], v[10:13], off offset:64 sc0 sc1
	s_waitcnt vmcnt(15)
	v_pk_fma_f32 v[8:9], v[8:9], v[126:127], v[218:219]
	v_pk_fma_f32 v[6:7], v[6:7], v[124:125], v[216:217]
	global_store_dwordx4 v[230:231], v[6:9], off offset:128 sc0 sc1
	s_waitcnt vmcnt(15)
	v_pk_fma_f32 v[4:5], v[4:5], v[130:131], v[222:223]
	v_pk_fma_f32 v[2:3], v[2:3], v[128:129], v[220:221]
	global_store_dwordx4 v[230:231], v[2:5], off offset:192 sc0 sc1
	s_cmp_lg_u32 s77, 9
	s_cbranch_scc1 .Ldep_nosig_k9
	v_readfirstlane_b32 s0, v74
	s_lshr_b32 s0, s0, 7
	s_lshl_b32 s0, s0, 2
	s_add_i32 s0, s0, 0x1e40
	v_writelane_b32 v250, s0, 42

; DI void modnorm_rows(const Params& p, int l, int which  , bool from_inputs, bool skip_ctx, int w0, int wstride, int lane) {
;   const float* g = (which ? p.norm2_g : p.norm1_g) + l * DM;
;   f32x4 gg[4];
; #pragma unroll
;   for (int i = 0; i < 4; ++i) gg[i] = *(const f32x4*)(g + i * 256 + lane * 4);
;   const int nrows = skip_ctx ? 8 * NLAT : T_TOK;
;   auto rowof = [&](int i) -> int { return skip_ctx ? (i / NLAT) * TB + NCTX + (i % NLAT) : i; };
;   int i = w0;
;   if (i >= nrows) return;
;   f32x4 vn[4];
;   {
;     const int row = rowof(i); const float* src = xsrc_row(p, from_inputs, row / TB, row % TB);
; #pragma unroll
;     for (int q = 0; q < 4; ++q) vn[q] = *(const f32x4*)(src + q * 256 + lane * 4);
.LBB0_228:
	s_andn2_b64 vcc, exec, s[0:1]
	s_cbranch_vccnz .LBB0_249
	v_readlane_b32 s0, v252, 9
	s_nop 1
	v_add_u32_e32 v1, s0, v158
	v_readlane_b32 s0, v250, 4
	v_readlane_b32 s1, v250, 5
	s_and_b64 s[0:1], s[0:1], exec
	s_movk_i32 s0, 0x4800
	s_cselect_b32 s26, 0x4000, s0
	v_cmp_gt_i32_e32 vcc, s26, v1
	s_and_saveexec_b64 s[2:3], vcc
	s_cbranch_execz .LBB0_248
	s_waitcnt vmcnt(0)
	s_barrier
	v_readlane_b32 s6, v250, 42
	s_nop 1
	s_cmp_eq_u32 s6, 0
	s_cbranch_scc1 .Lflush_none_norm2
	v_mov_b32_e32 v110, s6
	v_mov_b32_e32 v114, 1
	v_cmp_eq_u32_e32 vcc, 0, v138
	s_and_saveexec_b64 s[38:39], vcc
	global_atomic_add v110, v114, s[70:71]
	s_or_b64 exec, exec, s[38:39]
	s_mov_b32 s6, 0
	v_writelane_b32 v250, s6, 42
.Lflush_none_norm2:
	v_readlane_b32 s0, v252, 9
	v_lshlrev_b32_e32 v244, 4, v115
	v_lshlrev_b32_e32 v245, 3, v115
	v_add_u32_e32 v1, s0, v158
	s_nop 1
	v_readfirstlane_b32 s20, v1
	v_readlane_b32 s4, v254, 42
	v_readlane_b32 s5, v254, 43
	v_readlane_b32 s12, v254, 28
	v_readlane_b32 s13, v254, 29
	v_readlane_b32 s14, v254, 32
	v_readlane_b32 s15, v254, 33
	v_readlane_b32 s16, v253, 40
	v_readlane_b32 s17, v253, 41
	v_readlane_b32 s18, v250, 4
	v_readlane_b32 s19, v250, 5
	s_nop 3
	s_lshl_b32 s0, s49, 12
	s_add_u32 s4, s4, s0
	s_addc_u32 s5, s5, 0
	global_load_dwordx4 v[2:5], v244, s[4:5]
	global_load_dwordx4 v[6:9], v244, s[4:5] offset:1024
	global_load_dwordx4 v[10:13], v244, s[4:5] offset:2048
	global_load_dwordx4 v[14:17], v244, s[4:5] offset:3072
	s_mov_b32 s12, s56
	s_mov_b32 s13, s57
	s_mov_b32 s14, s64
	s_mov_b32 s15, s65
	s_cmp_lg_u64 s[18:19], 0
	s_cbranch_scc1 .Lnorm2_last
	s_mov_b32 s36, 0
	s_lshr_b32 s37, s20, 7
	s_and_b32 s37, s37, 15
	s_add_i32 s37, s37, 2
	s_lshr_b32 s37, s37, 1
	s_add_i32 s37, s37, 1
	s_cmp_ge_u32 s37, 9
	s_cselect_b32 s38, 9, 0
	s_sub_i32 s37, s37, s38
	s_add_i32 s6, s37, 0
	s_cmp_ge_u32 s6, 9
	s_cselect_b32 s38, 9, 0
	s_sub_i32 s6, s6, s38
	s_lshl_b32 s6, s6, 11
	s_add_i32 s6, s6, s20
	s_lshr_b32 s6, s6, 7
	s_lshl_b32 s6, s6, 2
	s_add_i32 s6, s6, 0x1c00
	v_mov_b32_e32 v110, s6
	global_load_dword v114, v110, s[70:71] sc1
	s_add_i32 s6, s37, 1
	s_cmp_ge_u32 s6, 9
	s_cselect_b32 s38, 9, 0
	s_sub_i32 s6, s6, s38
	s_lshl_b32 s6, s6, 11
	s_add_i32 s6, s6, s20
	s_lshr_b32 s6, s6, 7
	s_lshl_b32 s6, s6, 2
	s_add_i32 s6, s6, 0x1c00
	v_mov_b32_e32 v110, s6
	global_load_dword v116, v110, s[70:71] sc1
	s_add_i32 s6, s37, 2
	s_cmp_ge_u32 s6, 9
	s_cselect_b32 s38, 9, 0
	s_sub_i32 s6, s6, s38
	s_lshl_b32 s6, s6, 11
	s_add_i32 s6, s6, s20
	s_lshr_b32 s6, s6, 7
	s_lshl_b32 s6, s6, 2
	s_add_i32 s6, s6, 0x1c00
	v_mov_b32_e32 v110, s6
	global_load_dword v117, v110, s[70:71] sc1
	s_waitcnt vmcnt(2)
	v_readfirstlane_b32 s6, v114
	s_cmp_ge_u32 s6, 8
	s_cbranch_scc1 .Ldep_norm2a_ok0
	s_add_i32 s6, s37, 0
	s_cmp_ge_u32 s6, 9
	s_cselect_b32 s38, 9, 0
	s_sub_i32 s6, s6, s38
	s_lshl_b32 s6, s6, 11
	s_add_i32 s6, s6, s20
	s_lshr_b32 s6, s6, 7
	s_lshl_b32 s6, s6, 2
	s_add_i32 s6, s6, 0x1c00
	v_mov_b32_e32 v110, s6

; template <class Epi>
; DI void gemm_tile(const bf16_t* __restrict__ A, int lda, const bf16_t* __restrict__ Bt, int ldb, int K, int row0, int col0, char* lds, const Epi& epi) {
;     ...
;   for (int kt = 0; kt < KT; ++kt) {
;     asm volatile("s_waitcnt vmcnt(0)" ::: "memory");
;     __syncthreads();
;     const char* sa = lds + (kt & 1) * 32768 + (wr * 64 + fr) * 128;
;     const char* sb = lds + (kt & 1) * 32768 + 16384 + (wc * 64 + fr) * 128;
; #pragma unroll
;     for (int kk = 0; kk < 2; ++kk) {
;       if (kt + 1 < KT) { if (kk == 0) stage_a(kt + 1, (kt + 1) & 1); else stage_b(kt + 1, (kt + 1) & 1); }
;       bf16x8 a[4], b[4];
;       const int co = ((kk * 4 + fq) ^ swz) * 16;
; #pragma unroll
;       for (int m = 0; m < 4; ++m) a[m] = *(const bf16x8*)(sa + m * 2048 + co);
; #pragma unroll
;       for (int n = 0; n < 4; ++n) b[n] = *(const bf16x8*)(sb + n * 2048 + co);
; #pragma unroll
;       for (int m = 0; m < 4; ++m)
; #pragma unroll
;         for (int n = 0; n < 4; ++n) acc[m][n] = __builtin_amdgcn_mfma_f32_16x16x32_bf16(b[n], a[m], acc[m][n], 0, 0, 0);
;     }
;   }
.LBB0_267:
	s_add_i32 s20, s3, 0xffff8000
	s_and_b32 s29, s3, 0x8000
	s_and_b32 s20, s20, 0x8000
	v_add_u32_e32 v102, s29, v90
	v_add_u32_e32 v110, s20, v91
	v_or_b32_e32 v136, s20, v93
	v_add_u32_e32 v103, 0x1000, v102
	v_readfirstlane_b32 s20, v102
	v_lshl_add_u64 v[94:95], v[74:75], 0, s[0:1]
	v_add_u32_e32 v104, 0x2000, v102
	s_mov_b32 m0, s20
	v_readfirstlane_b32 s20, v103
	s_waitcnt vmcnt(0)
	s_waitcnt vmcnt(0) lgkmcnt(0)
	s_barrier
	v_lshl_add_u64 v[96:97], v[76:77], 0, s[0:1]
	v_add_u32_e32 v105, 0x3000, v102
	global_load_lds_dwordx4 v[94:95], off
	s_mov_b32 m0, s20
	v_readfirstlane_b32 s20, v104
	v_add_u32_e32 v137, 0x4000, v102
	v_lshl_add_u64 v[98:99], v[78:79], 0, s[0:1]
	global_load_lds_dwordx4 v[96:97], off
	s_mov_b32 m0, s20
	v_readfirstlane_b32 s20, v105
	v_add_u32_e32 v159, 0x5000, v102
	v_lshl_add_u64 v[100:101], v[80:81], 0, s[0:1]
	global_load_lds_dwordx4 v[98:99], off
	s_mov_b32 m0, s20
	v_readfirstlane_b32 s20, v137
	v_lshl_add_u64 v[132:133], v[66:67], 0, s[0:1]
	v_add_u32_e32 v160, 0x6000, v102
	global_load_lds_dwordx4 v[100:101], off
	v_add_u32_e32 v106, v110, v92
	v_add_u32_e32 v128, v136, v92
	s_mov_b32 m0, s20
	v_readfirstlane_b32 s20, v159
	v_lshl_add_u64 v[134:135], v[68:69], 0, s[0:1]
	v_add_u32_e32 v161, 0x7000, v102
	ds_read_b128 v[94:97], v106
	ds_read_b128 v[98:101], v106 offset:2048
	ds_read_b128 v[102:105], v106 offset:4096
	ds_read_b128 v[106:109], v106 offset:6144
	ds_read_b128 v[116:119], v128 offset:16384
	ds_read_b128 v[120:123], v128 offset:18432
	ds_read_b128 v[124:127], v128 offset:20480
	ds_read_b128 v[128:131], v128 offset:22528
	global_load_lds_dwordx4 v[132:133], off
	s_mov_b32 m0, s20
	v_readfirstlane_b32 s20, v160
	v_lshl_add_u64 v[84:85], v[70:71], 0, s[0:1]
	global_load_lds_dwordx4 v[134:135], off
	s_mov_b32 m0, s20
	v_readfirstlane_b32 s20, v161
	v_lshl_add_u64 v[82:83], v[72:73], 0, s[0:1]
	global_load_lds_dwordx4 v[84:85], off
	s_mov_b32 m0, s20
	s_waitcnt lgkmcnt(0)
	v_mfma_f32_16x16x32_bf16 v[30:33], v[116:119], v[102:105], v[30:33]
	global_load_lds_dwordx4 v[82:83], off
	s_add_u32 s0, s0, 0x80
	v_mfma_f32_16x16x32_bf16 v[26:29], v[120:123], v[102:105], v[26:29]
	s_addc_u32 s1, s1, 0
	s_add_i32 s3, s3, 0x8000
	s_cmpk_eq_i32 s0, 0x780
	v_mfma_f32_16x16x32_bf16 v[22:25], v[124:127], v[102:105], v[22:25]
	v_mfma_f32_16x16x32_bf16 v[18:21], v[128:131], v[102:105], v[18:21]
	v_add_u32_e32 v102, v110, v89
	v_add_u32_e32 v110, v136, v89
	v_mfma_f32_16x16x32_bf16 v[62:65], v[116:119], v[94:97], v[62:65]
	v_mfma_f32_16x16x32_bf16 v[58:61], v[120:123], v[94:97], v[58:61]
	v_mfma_f32_16x16x32_bf16 v[54:57], v[124:127], v[94:97], v[54:57]
	v_mfma_f32_16x16x32_bf16 v[50:53], v[128:131], v[94:97], v[50:53]
	v_mfma_f32_16x16x32_bf16 v[46:49], v[116:119], v[98:101], v[46:49]
	v_mfma_f32_16x16x32_bf16 v[42:45], v[120:123], v[98:101], v[42:45]
	v_mfma_f32_16x16x32_bf16 v[38:41], v[124:127], v[98:101], v[38:41]
	v_mfma_f32_16x16x32_bf16 v[34:37], v[128:131], v[98:101], v[34:37]
	ds_read_b128 v[82:85], v102
	ds_read_b128 v[94:97], v102 offset:2048
	ds_read_b128 v[98:101], v102 offset:4096
	ds_read_b128 v[102:105], v102 offset:6144
	v_mfma_f32_16x16x32_bf16 v[14:17], v[116:119], v[106:109], v[14:17]
	v_mfma_f32_16x16x32_bf16 v[10:13], v[120:123], v[106:109], v[10:13]
	v_mfma_f32_16x16x32_bf16 v[6:9], v[124:127], v[106:109], v[6:9]
	v_mfma_f32_16x16x32_bf16 v[2:5], v[128:131], v[106:109], v[2:5]
	ds_read_b128 v[106:109], v110 offset:16384
	ds_read_b128 v[116:119], v110 offset:18432
	ds_read_b128 v[120:123], v110 offset:20480
	ds_read_b128 v[124:127], v110 offset:22528
	s_waitcnt lgkmcnt(0)
	v_mfma_f32_16x16x32_bf16 v[62:65], v[106:109], v[82:85], v[62:65]
	v_mfma_f32_16x16x32_bf16 v[58:61], v[116:119], v[82:85], v[58:61]
	v_mfma_f32_16x16x32_bf16 v[54:57], v[120:123], v[82:85], v[54:57]
	v_mfma_f32_16x16x32_bf16 v[50:53], v[124:127], v[82:85], v[50:53]
	v_mfma_f32_16x16x32_bf16 v[46:49], v[106:109], v[94:97], v[46:49]
	v_mfma_f32_16x16x32_bf16 v[42:45], v[116:119], v[94:97], v[42:45]
	v_mfma_f32_16x16x32_bf16 v[38:41], v[120:123], v[94:97], v[38:41]
	v_mfma_f32_16x16x32_bf16 v[34:37], v[124:127], v[94:97], v[34:37]
	v_mfma_f32_16x16x32_bf16 v[30:33], v[106:109], v[98:101], v[30:33]
	v_mfma_f32_16x16x32_bf16 v[26:29], v[116:119], v[98:101], v[26:29]
	v_mfma_f32_16x16x32_bf16 v[22:25], v[120:123], v[98:101], v[22:25]
	v_mfma_f32_16x16x32_bf16 v[18:21], v[124:127], v[98:101], v[18:21]
	v_mfma_f32_16x16x32_bf16 v[14:17], v[106:109], v[102:105], v[14:17]
	v_mfma_f32_16x16x32_bf16 v[10:13], v[116:119], v[102:105], v[10:13]
	v_mfma_f32_16x16x32_bf16 v[6:9], v[120:123], v[102:105], v[6:9]
	v_mfma_f32_16x16x32_bf16 v[2:5], v[124:127], v[102:105], v[2:5]
	s_cbranch_scc0 .LBB0_267
	v_add_u32_e32 v90, s29, v93
	v_add_u32_e32 v91, s29, v91
	v_add_u32_e32 v82, v90, v92
	v_add_u32_e32 v92, v91, v92
	s_waitcnt vmcnt(0)
	s_waitcnt vmcnt(0)
	s_barrier
; template <class Epi>
; DI void gemm_tile(const bf16_t* __restrict__ A, int lda, const bf16_t* __restrict__ Bt, int ldb, int K, int row0, int col0, char* lds, const Epi& epi) {
;     ...
;       for (int m = 0; m < 4; ++m) a[m] = *(const bf16x8*)(sa + m * 2048 + co);
; #pragma unroll
;       for (int n = 0; n < 4; ++n) b[n] = *(const bf16x8*)(sb + n * 2048 + co);
; #pragma unroll
;       for (int m = 0; m < 4; ++m)
; #pragma unroll
;         for (int n = 0; n < 4; ++n) acc[m][n] = __builtin_amdgcn_mfma_f32_16x16x32_bf16(b[n], a[m], acc[m][n], 0, 0, 0);
;   DI void operator()(const f32x4 (&acc)[4][4], int r0, int c0, int fr, int fq) const {
; #pragma unroll
;     for (int m = 0; m < 4; ++m) {
;       const int row = r0 + m * 16 + fr; const int b = row / TB, s = row % TB;
;       const float* src = xsrc_row(*p, from_inputs, b, s);
;       float* dst = xdst_row(*p, b, s);
;       const float* gate = p->MOD + (size_t)(l * 9 + (s < NCTX ? 8 : b)) * 6144 + gate_off;
; #pragma unroll
;       for (int n = 0; n < 4; ++n) {
;         const int col = c0 + n * 16 + fq * 4;
;         f32x4 g = *(const f32x4*)(gate + col), xv = *(const f32x4*)(src + col);
	ds_read_b128 v[66:69], v82 offset:16384
	ds_read_b128 v[74:77], v82 offset:18432
	ds_read_b128 v[70:73], v92
	ds_read_b128 v[78:81], v82 offset:20480
	ds_read_b128 v[82:85], v82 offset:22528
	s_waitcnt lgkmcnt(2)
	v_mfma_f32_16x16x32_bf16 v[62:65], v[66:69], v[70:73], v[62:65]
	s_and_b64 vcc, exec, s[38:39]
	v_mfma_f32_16x16x32_bf16 v[58:61], v[74:77], v[70:73], v[58:61]
	s_waitcnt lgkmcnt(1)
	v_mfma_f32_16x16x32_bf16 v[54:57], v[78:81], v[70:73], v[54:57]
	s_waitcnt lgkmcnt(0)
	v_mfma_f32_16x16x32_bf16 v[50:53], v[82:85], v[70:73], v[50:53]
	ds_read_b128 v[70:73], v92 offset:2048
	s_waitcnt lgkmcnt(0)
	v_mfma_f32_16x16x32_bf16 v[46:49], v[66:69], v[70:73], v[46:49]
	v_mfma_f32_16x16x32_bf16 v[42:45], v[74:77], v[70:73], v[42:45]
	v_mfma_f32_16x16x32_bf16 v[38:41], v[78:81], v[70:73], v[38:41]
	v_mfma_f32_16x16x32_bf16 v[34:37], v[82:85], v[70:73], v[34:37]
	ds_read_b128 v[70:73], v92 offset:4096
	s_waitcnt lgkmcnt(0)
	v_mfma_f32_16x16x32_bf16 v[30:33], v[66:69], v[70:73], v[30:33]
	v_mfma_f32_16x16x32_bf16 v[26:29], v[74:77], v[70:73], v[26:29]
	v_mfma_f32_16x16x32_bf16 v[22:25], v[78:81], v[70:73], v[22:25]
	v_mfma_f32_16x16x32_bf16 v[18:21], v[82:85], v[70:73], v[18:21]
	ds_read_b128 v[70:73], v92 offset:6144
	s_waitcnt lgkmcnt(0)
	v_mfma_f32_16x16x32_bf16 v[10:13], v[74:77], v[70:73], v[10:13]
	v_add_u32_e32 v74, v90, v89
	v_add_u32_e32 v75, v91, v89
	ds_read_b128 v[90:93], v74 offset:22528
	v_mfma_f32_16x16x32_bf16 v[14:17], v[66:69], v[70:73], v[14:17]
	ds_read_b128 v[66:69], v74 offset:16384
	v_mfma_f32_16x16x32_bf16 v[6:9], v[78:81], v[70:73], v[6:9]
	ds_read_b128 v[76:79], v74 offset:18432
	v_mfma_f32_16x16x32_bf16 v[2:5], v[82:85], v[70:73], v[2:5]
	ds_read_b128 v[80:83], v74 offset:20480
	ds_read_b128 v[70:73], v75
	v_or_b32_e32 v74, s2, v87
	s_waitcnt lgkmcnt(0)
	v_mfma_f32_16x16x32_bf16 v[62:65], v[66:69], v[70:73], v[62:65]
	v_lshl_add_u32 v74, v88, 6, v74
	s_mov_b64 s[2:3], -1
	v_mfma_f32_16x16x32_bf16 v[58:61], v[76:79], v[70:73], v[58:61]
	v_mfma_f32_16x16x32_bf16 v[54:57], v[80:83], v[70:73], v[54:57]
	v_mfma_f32_16x16x32_bf16 v[50:53], v[90:93], v[70:73], v[50:53]
	ds_read_b128 v[70:73], v75 offset:2048
	s_waitcnt lgkmcnt(0)
	v_mfma_f32_16x16x32_bf16 v[46:49], v[66:69], v[70:73], v[46:49]
	v_mfma_f32_16x16x32_bf16 v[42:45], v[76:79], v[70:73], v[42:45]
	v_mfma_f32_16x16x32_bf16 v[38:41], v[80:83], v[70:73], v[38:41]
	v_mfma_f32_16x16x32_bf16 v[34:37], v[90:93], v[70:73], v[34:37]
	ds_read_b128 v[70:73], v75 offset:4096
	s_waitcnt lgkmcnt(0)
	v_mfma_f32_16x16x32_bf16 v[30:33], v[66:69], v[70:73], v[30:33]
	v_mfma_f32_16x16x32_bf16 v[26:29], v[76:79], v[70:73], v[26:29]
	v_mfma_f32_16x16x32_bf16 v[22:25], v[80:83], v[70:73], v[22:25]
	v_mfma_f32_16x16x32_bf16 v[18:21], v[90:93], v[70:73], v[18:21]
	ds_read_b128 v[70:73], v75 offset:6144
	s_waitcnt lgkmcnt(0)
	v_mfma_f32_16x16x32_bf16 v[14:17], v[66:69], v[70:73], v[14:17]
	v_mul_hi_i32 v66, v74, s47
	v_lshrrev_b32_e32 v67, 31, v66
	v_ashrrev_i32_e32 v66, 9, v66
	v_mfma_f32_16x16x32_bf16 v[10:13], v[76:79], v[70:73], v[10:13]
	v_add_u32_e32 v75, v66, v67
	v_mul_i32_i24_e32 v66, 0x900, v75
	v_sub_u32_e32 v67, v74, v66
	v_mfma_f32_16x16x32_bf16 v[6:9], v[80:83], v[70:73], v[6:9]
	v_cmp_lt_i32_e64 s[0:1], s33, v67
	v_mfma_f32_16x16x32_bf16 v[2:5], v[90:93], v[70:73], v[2:5]
	v_readlane_b32 s0, v250, 42
	s_nop 1
	s_cmp_eq_u32 s0, 0
	s_cbranch_scc1 .Ldep_nop_k6
	v_mov_b32_e32 v88, s0
	v_mov_b32_e32 v89, 1
	v_cmp_eq_u32_e32 vcc, 0, v138
	s_and_saveexec_b64 s[0:1], vcc
	global_atomic_add v88, v89, s[70:71]
	s_or_b64 exec, exec, s[0:1]
.Ldep_nop_k6:
	v_readlane_b32 s4, v254, 28
	v_readlane_b32 s5, v254, 29
	v_readlane_b32 s8, v254, 32
	v_readlane_b32 s9, v254, 33
	s_nop 3
	s_cmp_lg_u64 s[38:39], 0
	s_cselect_b32 s4, s56, s4
	s_cselect_b32 s5, s57, s5
	s_cselect_b32 s8, s64, s8
	s_cselect_b32 s9, s65, s9
	v_lshlrev_b32_e32 v1, 6, v1
	v_lshlrev_b32_e32 v67, 2, v86
	v_or3_b32 v80, v1, v67, s28
	v_lshlrev_b32_e32 v66, 2, v80
	v_mov_b32_e32 v67, 0
	v_mov_b32_e32 v100, s8
	v_mov_b32_e32 v101, s9
	v_mov_b32_e32 v102, s4
	v_mov_b32_e32 v103, s5
	v_mov_b32_e32 v104, s64
	v_mov_b32_e32 v105, s65
	v_mov_b32_e32 v106, s56
	v_mov_b32_e32 v107, s57
	s_add_u32 s0, s58, 0x2000
	s_addc_u32 s1, s59, 0
	v_mov_b32_e32 v108, s0
	v_mov_b32_e32 v109, s1
	v_mov_b32_e32 v110, 8
	v_mov_b32_e32 v88, v74
	v_mul_hi_i32 v89, v88, s47
	v_lshrrev_b32_e32 v90, 31, v89
	v_ashrrev_i32_e32 v89, 9, v89
	v_add_u32_e32 v91, v89, v90
	v_mul_i32_i24_e32 v89, 0x900, v91
	v_sub_u32_e32 v92, v88, v89
	v_cmp_lt_i32_e32 vcc, s33, v92
	v_lshlrev_b32_e32 v89, 11, v91
	v_add3_u32 v89, v92, v89, s75
	v_lshl_add_u32 v90, v91, 8, v92
	v_cndmask_b32_e32 v94, v90, v89, vcc
	v_ashrrev_i32_e32 v95, 31, v94
	v_lshlrev_b64 v[96:97], 12, v[94:95]
	v_lshl_add_u64 v[96:97], v[96:97], 0, v[66:67]
	v_cndmask_b32_e32 v98, v100, v102, vcc
	v_cndmask_b32_e32 v99, v101, v103, vcc
	v_lshl_add_u64 v[224:225], v[98:99], 0, v[96:97]
	v_cndmask_b32_e32 v98, v104, v106, vcc
	v_cndmask_b32_e32 v99, v105, v107, vcc
	v_lshl_add_u64 v[232:233], v[98:99], 0, v[96:97]
	v_cndmask_b32_e32 v93, v110, v91, vcc
	v_add_u32_e32 v93, s82, v93
	v_mad_i64_i32 v[240:241], s[0:1], v93, s24, v[108:109]
	s_nop 0
	v_lshl_add_u64 v[240:241], v[240:241], 0, v[66:67]
	global_load_dwordx4 v[116:119], v[240:241], off
	global_load_dwordx4 v[120:123], v[240:241], off offset:64
	global_load_dwordx4 v[124:127], v[240:241], off offset:128
	global_load_dwordx4 v[128:131], v[240:241], off offset:192
	global_load_dwordx4 v[160:163], v[224:225], off
	global_load_dwordx4 v[164:167], v[224:225], off offset:64
	global_load_dwordx4 v[168:171], v[224:225], off offset:128
;   DI void operator()(const f32x4 (&acc)[4][4], int r0, int c0, int fr, int fq) const {
; #pragma unroll
;     for (int m = 0; m < 4; ++m) {
;       const int row = r0 + m * 16 + fr; const int b = row / TB, s = row % TB;
;       const float* src = xsrc_row(*p, from_inputs, b, s);
;       float* dst = xdst_row(*p, b, s);
;       const float* gate = p->MOD + (size_t)(l * 9 + (s < NCTX ? 8 : b)) * 6144 + gate_off;
; #pragma unroll
;       for (int n = 0; n < 4; ++n) {
;         const int col = c0 + n * 16 + fq * 4;
;         f32x4 g = *(const f32x4*)(gate + col), xv = *(const f32x4*)(src + col);
;         *(f32x4*)(dst + col) = xv + g * acc[m][n];
;       }
;     }
	global_load_dwordx4 v[172:175], v[224:225], off offset:192
	v_or_b32_e32 v88, 16, v74
	v_mul_hi_i32 v89, v88, s47
	v_lshrrev_b32_e32 v90, 31, v89
	v_ashrrev_i32_e32 v89, 9, v89
	v_add_u32_e32 v91, v89, v90
	v_mul_i32_i24_e32 v89, 0x900, v91
	v_sub_u32_e32 v92, v88, v89
	v_cmp_lt_i32_e32 vcc, s33, v92
	v_lshlrev_b32_e32 v89, 11, v91
	v_add3_u32 v89, v92, v89, s75
	v_lshl_add_u32 v90, v91, 8, v92
	v_cndmask_b32_e32 v94, v90, v89, vcc
	v_ashrrev_i32_e32 v95, 31, v94
	v_lshlrev_b64 v[96:97], 12, v[94:95]
	v_lshl_add_u64 v[96:97], v[96:97], 0, v[66:67]
	v_cndmask_b32_e32 v98, v100, v102, vcc
	v_cndmask_b32_e32 v99, v101, v103, vcc
	v_lshl_add_u64 v[226:227], v[98:99], 0, v[96:97]
	v_cndmask_b32_e32 v98, v104, v106, vcc
	v_cndmask_b32_e32 v99, v105, v107, vcc
	v_lshl_add_u64 v[234:235], v[98:99], 0, v[96:97]
	global_load_dwordx4 v[176:179], v[226:227], off
	global_load_dwordx4 v[180:183], v[226:227], off offset:64
	global_load_dwordx4 v[184:187], v[226:227], off offset:128
	global_load_dwordx4 v[188:191], v[226:227], off offset:192
	v_or_b32_e32 v88, 32, v74
	v_mul_hi_i32 v89, v88, s47
	v_lshrrev_b32_e32 v90, 31, v89
	v_ashrrev_i32_e32 v89, 9, v89
	v_add_u32_e32 v91, v89, v90
	v_mul_i32_i24_e32 v89, 0x900, v91
	v_sub_u32_e32 v92, v88, v89
	v_cmp_lt_i32_e32 vcc, s33, v92
	v_lshlrev_b32_e32 v89, 11, v91
	v_add3_u32 v89, v92, v89, s75
	v_lshl_add_u32 v90, v91, 8, v92
	v_cndmask_b32_e32 v94, v90, v89, vcc
	v_ashrrev_i32_e32 v95, 31, v94
	v_lshlrev_b64 v[96:97], 12, v[94:95]
	v_lshl_add_u64 v[96:97], v[96:97], 0, v[66:67]
	v_cndmask_b32_e32 v98, v100, v102, vcc
	v_cndmask_b32_e32 v99, v101, v103, vcc
	v_lshl_add_u64 v[228:229], v[98:99], 0, v[96:97]
	v_cndmask_b32_e32 v98, v104, v106, vcc
	v_cndmask_b32_e32 v99, v105, v107, vcc
	v_lshl_add_u64 v[236:237], v[98:99], 0, v[96:97]
	global_load_dwordx4 v[192:195], v[228:229], off
	global_load_dwordx4 v[196:199], v[228:229], off offset:64
	global_load_dwordx4 v[200:203], v[228:229], off offset:128
	global_load_dwordx4 v[204:207], v[228:229], off offset:192
	v_or_b32_e32 v88, 48, v74
	v_mul_hi_i32 v89, v88, s47
	v_lshrrev_b32_e32 v90, 31, v89
	v_ashrrev_i32_e32 v89, 9, v89
	v_add_u32_e32 v91, v89, v90
	v_mul_i32_i24_e32 v89, 0x900, v91
	v_sub_u32_e32 v92, v88, v89
	v_cmp_lt_i32_e32 vcc, s33, v92
	v_lshlrev_b32_e32 v89, 11, v91
	v_add3_u32 v89, v92, v89, s75
	v_lshl_add_u32 v90, v91, 8, v92
	v_cndmask_b32_e32 v94, v90, v89, vcc
	v_ashrrev_i32_e32 v95, 31, v94
	v_lshlrev_b64 v[96:97], 12, v[94:95]
	v_lshl_add_u64 v[96:97], v[96:97], 0, v[66:67]
	v_cndmask_b32_e32 v98, v100, v102, vcc
	v_cndmask_b32_e32 v99, v101, v103, vcc
	v_lshl_add_u64 v[230:231], v[98:99], 0, v[96:97]
	v_cndmask_b32_e32 v98, v104, v106, vcc
	v_cndmask_b32_e32 v99, v105, v107, vcc
	v_lshl_add_u64 v[238:239], v[98:99], 0, v[96:97]
	global_load_dwordx4 v[208:211], v[230:231], off
	global_load_dwordx4 v[212:215], v[230:231], off offset:64
	global_load_dwordx4 v[216:219], v[230:231], off offset:128
	global_load_dwordx4 v[220:223], v[230:231], off offset:192
	s_waitcnt vmcnt(15)
	v_pk_fma_f32 v[64:65], v[64:65], v[118:119], v[162:163]
	v_pk_fma_f32 v[62:63], v[62:63], v[116:117], v[160:161]
	global_store_dwordx4 v[232:233], v[62:65], off sc0 sc1
	s_waitcnt vmcnt(15)
	v_pk_fma_f32 v[60:61], v[60:61], v[122:123], v[166:167]
	v_pk_fma_f32 v[58:59], v[58:59], v[120:121], v[164:165]
	global_store_dwordx4 v[232:233], v[58:61], off offset:64 sc0 sc1
	s_waitcnt vmcnt(15)
	v_pk_fma_f32 v[56:57], v[56:57], v[126:127], v[170:171]
	v_pk_fma_f32 v[54:55], v[54:55], v[124:125], v[168:169]
	global_store_dwordx4 v[232:233], v[54:57], off offset:128 sc0 sc1
	s_waitcnt vmcnt(15)
	v_pk_fma_f32 v[52:53], v[52:53], v[130:131], v[174:175]
	v_pk_fma_f32 v[50:51], v[50:51], v[128:129], v[172:173]
	global_store_dwordx4 v[232:233], v[50:53], off offset:192 sc0 sc1
	s_waitcnt vmcnt(15)
	v_pk_fma_f32 v[48:49], v[48:49], v[118:119], v[178:179]
	v_pk_fma_f32 v[46:47], v[46:47], v[116:117], v[176:177]
	global_store_dwordx4 v[234:235], v[46:49], off sc0 sc1
	s_waitcnt vmcnt(15)
	v_pk_fma_f32 v[44:45], v[44:45], v[122:123], v[182:183]
	v_pk_fma_f32 v[42:43], v[42:43], v[120:121], v[180:181]
	global_store_dwordx4 v[234:235], v[42:45], off offset:64 sc0 sc1
	s_waitcnt vmcnt(15)
	v_pk_fma_f32 v[40:41], v[40:41], v[126:127], v[186:187]
	v_pk_fma_f32 v[38:39], v[38:39], v[124:125], v[184:185]
	global_store_dwordx4 v[234:235], v[38:41], off offset:128 sc0 sc1
	s_waitcnt vmcnt(15)
	v_pk_fma_f32 v[36:37], v[36:37], v[130:131], v[190:191]
	v_pk_fma_f32 v[34:35], v[34:35], v[128:129], v[188:189]
	global_store_dwordx4 v[234:235], v[34:37], off offset:192 sc0 sc1
	s_waitcnt vmcnt(15)
	v_pk_fma_f32 v[32:33], v[32:33], v[118:119], v[194:195]
	v_pk_fma_f32 v[30:31], v[30:31], v[116:117], v[192:193]
	global_store_dwordx4 v[236:237], v[30:33], off sc0 sc1
	s_waitcnt vmcnt(15)
	v_pk_fma_f32 v[28:29], v[28:29], v[122:123], v[198:199]
	v_pk_fma_f32 v[26:27], v[26:27], v[120:121], v[196:197]
	global_store_dwordx4 v[236:237], v[26:29], off offset:64 sc0 sc1
	s_waitcnt vmcnt(15)
	v_pk_fma_f32 v[24:25], v[24:25], v[126:127], v[202:203]
	v_pk_fma_f32 v[22:23], v[22:23], v[124:125], v[200:201]
	global_store_dwordx4 v[236:237], v[22:25], off offset:128 sc0 sc1
	s_waitcnt vmcnt(15)
	v_pk_fma_f32 v[20:21], v[20:21], v[130:131], v[206:207]
	v_pk_fma_f32 v[18:19], v[18:19], v[128:129], v[204:205]
	global_store_dwordx4 v[236:237], v[18:21], off offset:192 sc0 sc1
	s_waitcnt vmcnt(15)
	v_pk_fma_f32 v[16:17], v[16:17], v[118:119], v[210:211]
	v_pk_fma_f32 v[14:15], v[14:15], v[116:117], v[208:209]
	global_store_dwordx4 v[238:239], v[14:17], off sc0 sc1
	s_waitcnt vmcnt(15)
	v_pk_fma_f32 v[12:13], v[12:13], v[122:123], v[214:215]
	v_pk_fma_f32 v[10:11], v[10:11], v[120:121], v[212:213]
	global_store_dwordx4 v[238:239], v[10:13], off offset:64 sc0 sc1
	s_waitcnt vmcnt(15)
	v_pk_fma_f32 v[8:9], v[8:9], v[126:127], v[218:219]
	v_pk_fma_f32 v[6:7], v[6:7], v[124:125], v[216:217]
	global_store_dwordx4 v[238:239], v[6:9], off offset:128 sc0 sc1
	s_waitcnt vmcnt(15)
	v_pk_fma_f32 v[4:5], v[4:5], v[130:131], v[222:223]
	v_pk_fma_f32 v[2:3], v[2:3], v[128:129], v[220:221]
	global_store_dwordx4 v[238:239], v[2:5], off offset:192 sc0 sc1
	s_cmp_lg_u32 s77, 6
	s_cbranch_scc1 .Ldep_nosig_k6
	v_readfirstlane_b32 s0, v74
	s_lshr_b32 s0, s0, 7
	s_lshl_b32 s0, s0, 2
	s_add_i32 s0, s0, 0x1c00
	v_writelane_b32 v250, s0, 42

; DI void modnorm_rows(const Params& p, int l, int which  , bool from_inputs, bool skip_ctx, int w0, int wstride, int lane) {
;   const float* g = (which ? p.norm2_g : p.norm1_g) + l * DM;
;   f32x4 gg[4];
; #pragma unroll
;   for (int i = 0; i < 4; ++i) gg[i] = *(const f32x4*)(g + i * 256 + lane * 4);
;   const int nrows = skip_ctx ? 8 * NLAT : T_TOK;
;   auto rowof = [&](int i) -> int { return skip_ctx ? (i / NLAT) * TB + NCTX + (i % NLAT) : i; };
;   int i = w0;
;   if (i >= nrows) return;
;   f32x4 vn[4];
;   {
;     const int row = rowof(i); const float* src = xsrc_row(p, from_inputs, row / TB, row % TB);
; #pragma unroll
;     for (int q = 0; q < 4; ++q) vn[q] = *(const f32x4*)(src + q * 256 + lane * 4);
;   }
;   for (; i < nrows; i += wstride) {
;     const int row = rowof(i); const int b = row / TB, s = row % TB;
;     f32x4 v[4];
; #pragma unroll
;     for (int q = 0; q < 4; ++q) v[q] = vn[q];
;     if (i + wstride < nrows) {
;       const int rn = rowof(i + wstride); const float* src = xsrc_row(p, from_inputs, rn / TB, rn % TB);
; #pragma unroll
;       for (int q = 0; q < 4; ++q) vn[q] = *(const f32x4*)(src + q * 256 + lane * 4);
;     }
;     const float* mod = p.MOD + (size_t)(l * 9 + (s < NCTX ? 8 : b)) * 6144 + (which ? 3 * 1024 : 0);
;     f32x4 sh[4], sc[4];
; #pragma unroll
;     for (int q = 0; q < 4; ++q) { sh[q] = *(const f32x4*)(mod + q * 256 + lane * 4); sc[q] = *(const f32x4*)(mod + 1024 + q * 256 + lane * 4); }
.LBB0_823:
	s_or_b64 exec, exec, s[0:1]
	v_readlane_b32 s0, v252, 9
	s_nop 1
	v_add_u32_e32 v50, s0, v158
	s_movk_i32 s0, 0x4800
	v_cmp_gt_i32_e32 vcc, s0, v50
	s_and_saveexec_b64 s[2:3], vcc
	s_cbranch_execz .LBB0_852
	s_waitcnt vmcnt(0)
	s_barrier
	v_readlane_b32 s6, v250, 42
	s_nop 1
	s_cmp_eq_u32 s6, 0
	s_cbranch_scc1 .Lflush_none_norm1
	v_mov_b32_e32 v110, s6
	v_mov_b32_e32 v114, 1
	v_cmp_eq_u32_e32 vcc, 0, v138
	s_and_saveexec_b64 s[38:39], vcc
	global_atomic_add v110, v114, s[70:71]
	s_or_b64 exec, exec, s[38:39]
	s_mov_b32 s6, 0
	v_writelane_b32 v250, s6, 42
.Lflush_none_norm1:
	v_readlane_b32 s0, v252, 9
	v_lshlrev_b32_e32 v244, 4, v115
	v_lshlrev_b32_e32 v245, 3, v115
	v_add_u32_e32 v1, s0, v158
	s_nop 1
	v_readfirstlane_b32 s20, v1
	v_readlane_b32 s4, v254, 40
	v_readlane_b32 s5, v254, 41
	v_readlane_b32 s12, v254, 28
	v_readlane_b32 s13, v254, 29
	v_readlane_b32 s14, v254, 32
	v_readlane_b32 s15, v254, 33
	v_readlane_b32 s16, v253, 40
	v_readlane_b32 s17, v253, 41
	v_readlane_b32 s18, v250, 4
	v_readlane_b32 s19, v250, 5
	s_nop 3
	s_lshl_b32 s0, s49, 12
	s_add_u32 s4, s4, s0
	s_addc_u32 s5, s5, 0
	global_load_dwordx4 v[2:5], v244, s[4:5]
	global_load_dwordx4 v[6:9], v244, s[4:5] offset:1024
	global_load_dwordx4 v[10:13], v244, s[4:5] offset:2048
	global_load_dwordx4 v[14:17], v244, s[4:5] offset:3072
	s_add_i32 s0, s77, 7
	s_cmp_gt_u32 s0, 16
	s_cselect_b32 s12, s56, s12
	s_cselect_b32 s13, s57, s13
	s_cselect_b32 s14, s64, s14
	s_cselect_b32 s15, s65, s15
	s_cmp_gt_u32 s77, 9
	s_cbranch_scc1 .Lnorm1_l1
	s_add_i32 s21, s20, 0
	s_mul_hi_u32 s7, s21, 0x38e38e39
	s_lshr_b32 s7, s7, 9
	s_mul_i32 s8, s7, 0x900
	s_sub_i32 s8, s21, s8
	s_lshl_b32 s9, s7, 11
	s_add_i32 s9, s9, s8
	s_add_i32 s9, s9, 0xffffff00
	s_lshl_b32 s10, s7, 8
	s_add_i32 s10, s10, s8
	s_cmpk_gt_i32 s8, 0xff
	s_cselect_b32 s9, s9, s10
	s_cselect_b32 s26, s12, s14
	s_cselect_b32 s27, s13, s15
	s_cselect_b32 s10, s7, 8
	s_lshl_b32 s9, s9, 12
	s_add_u32 s26, s26, s9
	s_addc_u32 s27, s27, 0
	s_add_i32 s10, s10, s82
	s_mul_i32 s10, s10, s24
	s_add_u32 s28, s58, s10
	s_addc_u32 s29, s59, 0
	s_add_u32 s28, s28, 0x0
	s_addc_u32 s29, s29, 0
	s_add_u32 s0, s28, 0x1000
	s_addc_u32 s1, s29, 0
	global_load_dwordx4 v[18:21], v244, s[26:27]
	global_load_dwordx4 v[22:25], v244, s[26:27] offset:1024
	global_load_dwordx4 v[26:29], v244, s[26:27] offset:2048
	global_load_dwordx4 v[30:33], v244, s[26:27] offset:3072
	global_load_dwordx4 v[34:37], v244, s[28:29]
	global_load_dwordx4 v[38:41], v244, s[28:29] offset:1024
	global_load_dwordx4 v[42:45], v244, s[28:29] offset:2048
	global_load_dwordx4 v[46:49], v244, s[28:29] offset:3072
	global_load_dwordx4 v[50:53], v244, s[0:1]
	global_load_dwordx4 v[54:57], v244, s[0:1] offset:1024
	global_load_dwordx4 v[58:61], v244, s[0:1] offset:2048
	global_load_dwordx4 v[62:65], v244, s[0:1] offset:3072
	s_add_i32 s21, s20, 2048
	s_mul_hi_u32 s7, s21, 0x38e38e39
	s_lshr_b32 s7, s7, 9
	s_mul_i32 s8, s7, 0x900
	s_sub_i32 s8, s21, s8
	s_lshl_b32 s9, s7, 11
	s_add_i32 s9, s9, s8
	s_add_i32 s9, s9, 0xffffff00
	s_lshl_b32 s10, s7, 8
	s_add_i32 s10, s10, s8
	s_cmpk_gt_i32 s8, 0xff
	s_cselect_b32 s9, s9, s10
	s_cselect_b32 s26, s12, s14
	s_cselect_b32 s27, s13, s15
	s_cselect_b32 s10, s7, 8
	s_lshl_b32 s9, s9, 12
	s_add_u32 s26, s26, s9
	s_addc_u32 s27, s27, 0
	s_add_i32 s10, s10, s82
	s_mul_i32 s10, s10, s24
	s_add_u32 s28, s58, s10
	s_addc_u32 s29, s59, 0
	s_add_u32 s28, s28, 0x0
	s_addc_u32 s29, s29, 0
	s_add_u32 s0, s28, 0x1000
	s_addc_u32 s1, s29, 0
	global_load_dwordx4 v[66:69], v244, s[26:27]
	global_load_dwordx4 v[70:73], v244, s[26:27] offset:1024
	global_load_dwordx4 v[74:77], v244, s[26:27] offset:2048
	global_load_dwordx4 v[78:81], v244, s[26:27] offset:3072
	global_load_dwordx4 v[82:85], v244, s[28:29]
	global_load_dwordx4 v[86:89], v244, s[28:29] offset:1024
	global_load_dwordx4 v[90:93], v244, s[28:29] offset:2048
	global_load_dwordx4 v[94:97], v244, s[28:29] offset:3072
	global_load_dwordx4 v[98:101], v244, s[0:1]
	global_load_dwordx4 v[102:105], v244, s[0:1] offset:1024
	global_load_dwordx4 v[106:109], v244, s[0:1] offset:2048
	global_load_dwordx4 v[118:121], v244, s[0:1] offset:3072
	s_add_i32 s21, s20, 4096
	s_mul_hi_u32 s7, s21, 0x38e38e39
	s_lshr_b32 s7, s7, 9
	s_mul_i32 s8, s7, 0x900
	s_sub_i32 s8, s21, s8
	s_lshl_b32 s9, s7, 11
	s_add_i32 s9, s9, s8
	s_add_i32 s9, s9, 0xffffff00
	s_lshl_b32 s10, s7, 8
	s_add_i32 s10, s10, s8
	s_cmpk_gt_i32 s8, 0xff
	s_cselect_b32 s9, s9, s10
	s_cselect_b32 s26, s12, s14
	s_cselect_b32 s27, s13, s15
	s_cselect_b32 s10, s7, 8
	s_lshl_b32 s9, s9, 12
	s_add_u32 s26, s26, s9
	s_addc_u32 s27, s27, 0
	s_add_i32 s10, s10, s82
	s_mul_i32 s10, s10, s24
	s_add_u32 s28, s58, s10
	s_addc_u32 s29, s59, 0
	s_add_u32 s28, s28, 0x0
	s_addc_u32 s29, s29, 0
	s_add_u32 s0, s28, 0x1000
	s_addc_u32 s1, s29, 0
	global_load_dwordx4 v[122:125], v244, s[26:27]
	global_load_dwordx4 v[126:129], v244, s[26:27] offset:1024
	global_load_dwordx4 v[130:133], v244, s[26:27] offset:2048
	global_load_dwordx4 v[134:137], v244, s[26:27] offset:3072
	global_load_dwordx4 v[160:163], v244, s[28:29]
	global_load_dwordx4 v[164:167], v244, s[28:29] offset:1024
	global_load_dwordx4 v[168:171], v244, s[28:29] offset:2048
	global_load_dwordx4 v[172:175], v244, s[28:29] offset:3072
	global_load_dwordx4 v[176:179], v244, s[0:1]
	global_load_dwordx4 v[180:183], v244, s[0:1] offset:1024
	global_load_dwordx4 v[184:187], v244, s[0:1] offset:2048
	global_load_dwordx4 v[188:191], v244, s[0:1] offset:3072
	s_waitcnt vmcnt(24)
; DI unsigned pk_bf16(float lo, float hi) { f32x2 v = {lo, hi}; bf16v2 b = __builtin_convertvector(v, bf16v2); return __builtin_bit_cast(unsigned, b); }
; DI float red64(float x) { for (int o = 32; o > 0; o >>= 1) x += __shfl_xor(x, o); return x; }
; DI void modnorm_rows(const Params& p, int l, int which  , bool from_inputs, bool skip_ctx, int w0, int wstride, int lane) {
;     ...
;   for (; i < nrows; i += wstride) {
;     const int row = rowof(i); const int b = row / TB, s = row % TB;
;     f32x4 v[4];
; #pragma unroll
;     for (int q = 0; q < 4; ++q) v[q] = vn[q];
;     if (i + wstride < nrows) {
;       const int rn = rowof(i + wstride); const float* src = xsrc_row(p, from_inputs, rn / TB, rn % TB);
; #pragma unroll
;       for (int q = 0; q < 4; ++q) vn[q] = *(const f32x4*)(src + q * 256 + lane * 4);
;     }
;     const float* mod = p.MOD + (size_t)(l * 9 + (s < NCTX ? 8 : b)) * 6144 + (which ? 3 * 1024 : 0);
;     f32x4 sh[4], sc[4];
; #pragma unroll
;     for (int q = 0; q < 4; ++q) { sh[q] = *(const f32x4*)(mod + q * 256 + lane * 4); sc[q] = *(const f32x4*)(mod + 1024 + q * 256 + lane * 4); }
;     float ss = 0.f;
; #pragma unroll
;     for (int q = 0; q < 4; ++q) ss += v[q][0] * v[q][0] + v[q][1] * v[q][1] + v[q][2] * v[q][2] + v[q][3] * v[q][3];
;     ss = red64(ss);
;     const float rs = rsqrtf(ss * (1.f / 1024.f) + EPSF);
;     bf16_t* dst = p.HY + (size_t)row * DM;
; #pragma unroll
;     for (int q = 0; q < 4; ++q) {
;       float o[4];
; #pragma unroll
;       for (int j = 0; j < 4; ++j) o[j] = (v[q][j] * rs * gg[q][j]) * (1.f + sc[q][j]) + sh[q][j];
;       u32x2 w = {pk_bf16(o[0], o[1]), pk_bf16(o[2], o[3])};
;       *(u32x2*)(dst + q * 256 + lane * 4) = w;
;     }
	v_pk_mul_f32 v[246:247], v[18:19], v[18:19]
	v_pk_fma_f32 v[246:247], v[20:21], v[20:21], v[246:247]
	v_pk_fma_f32 v[246:247], v[22:23], v[22:23], v[246:247]
	v_pk_fma_f32 v[246:247], v[24:25], v[24:25], v[246:247]
	v_pk_fma_f32 v[246:247], v[26:27], v[26:27], v[246:247]
	v_pk_fma_f32 v[246:247], v[28:29], v[28:29], v[246:247]
	v_pk_fma_f32 v[246:247], v[30:31], v[30:31], v[246:247]
	v_pk_fma_f32 v[246:247], v[32:33], v[32:33], v[246:247]
	s_nop 0
	v_add_f32_e32 v246, v246, v247
	s_nop 1
	v_add_f32_dpp v246, v246, v246 quad_perm:[1,0,3,2] row_mask:0xf bank_mask:0xf
	s_nop 1
	v_add_f32_dpp v246, v246, v246 quad_perm:[2,3,0,1] row_mask:0xf bank_mask:0xf
	s_nop 1
	v_add_f32_dpp v246, v246, v246 row_half_mirror row_mask:0xf bank_mask:0xf
	s_nop 1
	v_add_f32_dpp v246, v246, v246 row_mirror row_mask:0xf bank_mask:0xf
	s_nop 1
	v_add_f32_dpp v246, v246, v246 row_bcast:15 row_mask:0xa bank_mask:0xf
	s_nop 1
	v_add_f32_dpp v246, v246, v246 row_bcast:31 row_mask:0xc bank_mask:0xf
	s_nop 1
	v_readlane_b32 s0, v246, 63
	s_add_i32 s21, s20, 0
	s_lshl_b32 s21, s21, 11
	s_add_u32 s10, s16, s21
	s_addc_u32 s11, s17, 0
	v_mov_b32_e32 v248, s0
	v_fmamk_f32 v248, v248, 0x3a800000, v143
	v_rsq_f32_e32 v248, v248
	s_nop 0
	v_pk_mul_f32 v[18:19], v[18:19], v[248:249] op_sel_hi:[1,0]
	v_pk_add_f32 v[50:51], v[50:51], 1.0 op_sel_hi:[1,0]
	v_pk_mul_f32 v[18:19], v[2:3], v[18:19]
	v_pk_fma_f32 v[18:19], v[50:51], v[18:19], v[34:35]
	v_pk_mul_f32 v[20:21], v[20:21], v[248:249] op_sel_hi:[1,0]
	v_pk_add_f32 v[52:53], v[52:53], 1.0 op_sel_hi:[1,0]
	v_pk_mul_f32 v[20:21], v[4:5], v[20:21]
	v_pk_fma_f32 v[20:21], v[52:53], v[20:21], v[36:37]
	v_cvt_pk_bf16_f32 v34, v18, v19
	v_cvt_pk_bf16_f32 v35, v20, v21
	global_store_dwordx2 v245, v[34:35], s[10:11]
	v_pk_mul_f32 v[22:23], v[22:23], v[248:249] op_sel_hi:[1,0]
	v_pk_add_f32 v[54:55], v[54:55], 1.0 op_sel_hi:[1,0]
	v_pk_mul_f32 v[22:23], v[6:7], v[22:23]
	v_pk_fma_f32 v[22:23], v[54:55], v[22:23], v[38:39]
	v_pk_mul_f32 v[24:25], v[24:25], v[248:249] op_sel_hi:[1,0]
	v_pk_add_f32 v[56:57], v[56:57], 1.0 op_sel_hi:[1,0]
	v_pk_mul_f32 v[24:25], v[8:9], v[24:25]
	v_pk_fma_f32 v[24:25], v[56:57], v[24:25], v[40:41]
	v_cvt_pk_bf16_f32 v38, v22, v23
	v_cvt_pk_bf16_f32 v39, v24, v25
	global_store_dwordx2 v245, v[38:39], s[10:11] offset:512
	v_pk_mul_f32 v[26:27], v[26:27], v[248:249] op_sel_hi:[1,0]
	v_pk_add_f32 v[58:59], v[58:59], 1.0 op_sel_hi:[1,0]
	v_pk_mul_f32 v[26:27], v[10:11], v[26:27]
	v_pk_fma_f32 v[26:27], v[58:59], v[26:27], v[42:43]
	v_pk_mul_f32 v[28:29], v[28:29], v[248:249] op_sel_hi:[1,0]
	v_pk_add_f32 v[60:61], v[60:61], 1.0 op_sel_hi:[1,0]
	v_pk_mul_f32 v[28:29], v[12:13], v[28:29]
	v_pk_fma_f32 v[28:29], v[60:61], v[28:29], v[44:45]
	v_cvt_pk_bf16_f32 v42, v26, v27
	v_cvt_pk_bf16_f32 v43, v28, v29
	global_store_dwordx2 v245, v[42:43], s[10:11] offset:1024
	v_pk_mul_f32 v[30:31], v[30:31], v[248:249] op_sel_hi:[1,0]
	v_pk_add_f32 v[62:63], v[62:63], 1.0 op_sel_hi:[1,0]
	v_pk_mul_f32 v[30:31], v[14:15], v[30:31]
	v_pk_fma_f32 v[30:31], v[62:63], v[30:31], v[46:47]
	v_pk_mul_f32 v[32:33], v[32:33], v[248:249] op_sel_hi:[1,0]
	v_pk_add_f32 v[64:65], v[64:65], 1.0 op_sel_hi:[1,0]
	v_pk_mul_f32 v[32:33], v[16:17], v[32:33]
	v_pk_fma_f32 v[32:33], v[64:65], v[32:33], v[48:49]
	v_cvt_pk_bf16_f32 v46, v30, v31
	v_cvt_pk_bf16_f32 v47, v32, v33
	global_store_dwordx2 v245, v[46:47], s[10:11] offset:1536
	s_add_i32 s21, s20, 6144
	s_mul_hi_u32 s7, s21, 0x38e38e39
	s_lshr_b32 s7, s7, 9
	s_mul_i32 s8, s7, 0x900
	s_sub_i32 s8, s21, s8
	s_lshl_b32 s9, s7, 11
	s_add_i32 s9, s9, s8
	s_add_i32 s9, s9, 0xffffff00
	s_lshl_b32 s10, s7, 8
	s_add_i32 s10, s10, s8
	s_cmpk_gt_i32 s8, 0xff
	s_cselect_b32 s9, s9, s10
	s_cselect_b32 s26, s12, s14
	s_cselect_b32 s27, s13, s15
	s_cselect_b32 s10, s7, 8
	s_lshl_b32 s9, s9, 12
	s_add_u32 s26, s26, s9
	s_addc_u32 s27, s27, 0
	s_add_i32 s10, s10, s82
	s_mul_i32 s10, s10, s24
	s_add_u32 s28, s58, s10
	s_addc_u32 s29, s59, 0
	s_add_u32 s28, s28, 0x0
	s_addc_u32 s29, s29, 0
	s_add_u32 s0, s28, 0x1000
	s_addc_u32 s1, s29, 0
	global_load_dwordx4 v[18:21], v244, s[26:27]
	global_load_dwordx4 v[22:25], v244, s[26:27] offset:1024
	global_load_dwordx4 v[26:29], v244, s[26:27] offset:2048
	global_load_dwordx4 v[30:33], v244, s[26:27] offset:3072
	global_load_dwordx4 v[34:37], v244, s[28:29]
	global_load_dwordx4 v[38:41], v244, s[28:29] offset:1024
	global_load_dwordx4 v[42:45], v244, s[28:29] offset:2048
	global_load_dwordx4 v[46:49], v244, s[28:29] offset:3072
	global_load_dwordx4 v[50:53], v244, s[0:1]
	global_load_dwordx4 v[54:57], v244, s[0:1] offset:1024
	global_load_dwordx4 v[58:61], v244, s[0:1] offset:2048
	global_load_dwordx4 v[62:65], v244, s[0:1] offset:3072
	s_waitcnt vmcnt(28)
; DI unsigned pk_bf16(float lo, float hi) { f32x2 v = {lo, hi}; bf16v2 b = __builtin_convertvector(v, bf16v2); return __builtin_bit_cast(unsigned, b); }
; DI float red64(float x) { for (int o = 32; o > 0; o >>= 1) x += __shfl_xor(x, o); return x; }
; DI void modnorm_rows(const Params& p, int l, int which  , bool from_inputs, bool skip_ctx, int w0, int wstride, int lane) {
;     ...
;   for (; i < nrows; i += wstride) {
;     const int row = rowof(i); const int b = row / TB, s = row % TB;
;     f32x4 v[4];
; #pragma unroll
;     for (int q = 0; q < 4; ++q) v[q] = vn[q];
;     if (i + wstride < nrows) {
;       const int rn = rowof(i + wstride); const float* src = xsrc_row(p, from_inputs, rn / TB, rn % TB);
; #pragma unroll
;       for (int q = 0; q < 4; ++q) vn[q] = *(const f32x4*)(src + q * 256 + lane * 4);
;     }
;     const float* mod = p.MOD + (size_t)(l * 9 + (s < NCTX ? 8 : b)) * 6144 + (which ? 3 * 1024 : 0);
;     f32x4 sh[4], sc[4];
; #pragma unroll
;     for (int q = 0; q < 4; ++q) { sh[q] = *(const f32x4*)(mod + q * 256 + lane * 4); sc[q] = *(const f32x4*)(mod + 1024 + q * 256 + lane * 4); }
;     float ss = 0.f;
; #pragma unroll
;     for (int q = 0; q < 4; ++q) ss += v[q][0] * v[q][0] + v[q][1] * v[q][1] + v[q][2] * v[q][2] + v[q][3] * v[q][3];
;     ss = red64(ss);
;     const float rs = rsqrtf(ss * (1.f / 1024.f) + EPSF);
;     bf16_t* dst = p.HY + (size_t)row * DM;
; #pragma unroll
;     for (int q = 0; q < 4; ++q) {
;       float o[4];
; #pragma unroll
;       for (int j = 0; j < 4; ++j) o[j] = (v[q][j] * rs * gg[q][j]) * (1.f + sc[q][j]) + sh[q][j];
;       u32x2 w = {pk_bf16(o[0], o[1]), pk_bf16(o[2], o[3])};
;       *(u32x2*)(dst + q * 256 + lane * 4) = w;
;     }
	v_pk_mul_f32 v[246:247], v[66:67], v[66:67]
	v_pk_fma_f32 v[246:247], v[68:69], v[68:69], v[246:247]
	v_pk_fma_f32 v[246:247], v[70:71], v[70:71], v[246:247]
	v_pk_fma_f32 v[246:247], v[72:73], v[72:73], v[246:247]
	v_pk_fma_f32 v[246:247], v[74:75], v[74:75], v[246:247]
	v_pk_fma_f32 v[246:247], v[76:77], v[76:77], v[246:247]
	v_pk_fma_f32 v[246:247], v[78:79], v[78:79], v[246:247]
	v_pk_fma_f32 v[246:247], v[80:81], v[80:81], v[246:247]
	s_nop 0
	v_add_f32_e32 v246, v246, v247
	s_nop 1
	v_add_f32_dpp v246, v246, v246 quad_perm:[1,0,3,2] row_mask:0xf bank_mask:0xf
	s_nop 1
	v_add_f32_dpp v246, v246, v246 quad_perm:[2,3,0,1] row_mask:0xf bank_mask:0xf
	s_nop 1
	v_add_f32_dpp v246, v246, v246 row_half_mirror row_mask:0xf bank_mask:0xf
	s_nop 1
	v_add_f32_dpp v246, v246, v246 row_mirror row_mask:0xf bank_mask:0xf
	s_nop 1
	v_add_f32_dpp v246, v246, v246 row_bcast:15 row_mask:0xa bank_mask:0xf
	s_nop 1
	v_add_f32_dpp v246, v246, v246 row_bcast:31 row_mask:0xc bank_mask:0xf
	s_nop 1
	v_readlane_b32 s0, v246, 63
	s_add_i32 s21, s20, 2048
	s_lshl_b32 s21, s21, 11
	s_add_u32 s10, s16, s21
	s_addc_u32 s11, s17, 0
	v_mov_b32_e32 v248, s0
	v_fmamk_f32 v248, v248, 0x3a800000, v143
	v_rsq_f32_e32 v248, v248
	s_nop 0
	v_pk_mul_f32 v[66:67], v[66:67], v[248:249] op_sel_hi:[1,0]
	v_pk_add_f32 v[98:99], v[98:99], 1.0 op_sel_hi:[1,0]
	v_pk_mul_f32 v[66:67], v[2:3], v[66:67]
	v_pk_fma_f32 v[66:67], v[98:99], v[66:67], v[82:83]
	v_pk_mul_f32 v[68:69], v[68:69], v[248:249] op_sel_hi:[1,0]
	v_pk_add_f32 v[100:101], v[100:101], 1.0 op_sel_hi:[1,0]
	v_pk_mul_f32 v[68:69], v[4:5], v[68:69]
	v_pk_fma_f32 v[68:69], v[100:101], v[68:69], v[84:85]
	v_cvt_pk_bf16_f32 v82, v66, v67
	v_cvt_pk_bf16_f32 v83, v68, v69
	global_store_dwordx2 v245, v[82:83], s[10:11]
	v_pk_mul_f32 v[70:71], v[70:71], v[248:249] op_sel_hi:[1,0]
	v_pk_add_f32 v[102:103], v[102:103], 1.0 op_sel_hi:[1,0]
	v_pk_mul_f32 v[70:71], v[6:7], v[70:71]
	v_pk_fma_f32 v[70:71], v[102:103], v[70:71], v[86:87]
	v_pk_mul_f32 v[72:73], v[72:73], v[248:249] op_sel_hi:[1,0]
	v_pk_add_f32 v[104:105], v[104:105], 1.0 op_sel_hi:[1,0]
	v_pk_mul_f32 v[72:73], v[8:9], v[72:73]
	v_pk_fma_f32 v[72:73], v[104:105], v[72:73], v[88:89]
	v_cvt_pk_bf16_f32 v86, v70, v71
	v_cvt_pk_bf16_f32 v87, v72, v73
	global_store_dwordx2 v245, v[86:87], s[10:11] offset:512
	v_pk_mul_f32 v[74:75], v[74:75], v[248:249] op_sel_hi:[1,0]
	v_pk_add_f32 v[106:107], v[106:107], 1.0 op_sel_hi:[1,0]
	v_pk_mul_f32 v[74:75], v[10:11], v[74:75]
	v_pk_fma_f32 v[74:75], v[106:107], v[74:75], v[90:91]
	v_pk_mul_f32 v[76:77], v[76:77], v[248:249] op_sel_hi:[1,0]
	v_pk_add_f32 v[108:109], v[108:109], 1.0 op_sel_hi:[1,0]
	v_pk_mul_f32 v[76:77], v[12:13], v[76:77]
	v_pk_fma_f32 v[76:77], v[108:109], v[76:77], v[92:93]
	v_cvt_pk_bf16_f32 v90, v74, v75
	v_cvt_pk_bf16_f32 v91, v76, v77
	global_store_dwordx2 v245, v[90:91], s[10:11] offset:1024
	v_pk_mul_f32 v[78:79], v[78:79], v[248:249] op_sel_hi:[1,0]
	v_pk_add_f32 v[118:119], v[118:119], 1.0 op_sel_hi:[1,0]
	v_pk_mul_f32 v[78:79], v[14:15], v[78:79]
	v_pk_fma_f32 v[78:79], v[118:119], v[78:79], v[94:95]
	v_pk_mul_f32 v[80:81], v[80:81], v[248:249] op_sel_hi:[1,0]
	v_pk_add_f32 v[120:121], v[120:121], 1.0 op_sel_hi:[1,0]
	v_pk_mul_f32 v[80:81], v[16:17], v[80:81]
	v_pk_fma_f32 v[80:81], v[120:121], v[80:81], v[96:97]
	v_cvt_pk_bf16_f32 v94, v78, v79
	v_cvt_pk_bf16_f32 v95, v80, v81
	global_store_dwordx2 v245, v[94:95], s[10:11] offset:1536
	s_add_i32 s21, s20, 8192
	s_mul_hi_u32 s7, s21, 0x38e38e39
	s_lshr_b32 s7, s7, 9
	s_mul_i32 s8, s7, 0x900
	s_sub_i32 s8, s21, s8
	s_lshl_b32 s9, s7, 11
	s_add_i32 s9, s9, s8
	s_add_i32 s9, s9, 0xffffff00
	s_lshl_b32 s10, s7, 8
	s_add_i32 s10, s10, s8
	s_cmpk_gt_i32 s8, 0xff
	s_cselect_b32 s9, s9, s10
	s_cselect_b32 s26, s12, s14
	s_cselect_b32 s27, s13, s15
	s_cselect_b32 s10, s7, 8
	s_lshl_b32 s9, s9, 12
	s_add_u32 s26, s26, s9
	s_addc_u32 s27, s27, 0
	s_add_i32 s10, s10, s82
	s_mul_i32 s10, s10, s24
	s_add_u32 s28, s58, s10
	s_addc_u32 s29, s59, 0
	s_add_u32 s28, s28, 0x0
	s_addc_u32 s29, s29, 0
	s_add_u32 s0, s28, 0x1000
	s_addc_u32 s1, s29, 0
	global_load_dwordx4 v[66:69], v244, s[26:27]
	global_load_dwordx4 v[70:73], v244, s[26:27] offset:1024
	global_load_dwordx4 v[74:77], v244, s[26:27] offset:2048
	global_load_dwordx4 v[78:81], v244, s[26:27] offset:3072
	global_load_dwordx4 v[82:85], v244, s[28:29]
	global_load_dwordx4 v[86:89], v244, s[28:29] offset:1024
	global_load_dwordx4 v[90:93], v244, s[28:29] offset:2048
	global_load_dwordx4 v[94:97], v244, s[28:29] offset:3072
	global_load_dwordx4 v[98:101], v244, s[0:1]
	global_load_dwordx4 v[102:105], v244, s[0:1] offset:1024
	global_load_dwordx4 v[106:109], v244, s[0:1] offset:2048
	global_load_dwordx4 v[118:121], v244, s[0:1] offset:3072
	s_waitcnt vmcnt(32)
; DI unsigned pk_bf16(float lo, float hi) { f32x2 v = {lo, hi}; bf16v2 b = __builtin_convertvector(v, bf16v2); return __builtin_bit_cast(unsigned, b); }
; DI float red64(float x) { for (int o = 32; o > 0; o >>= 1) x += __shfl_xor(x, o); return x; }
; DI void modnorm_rows(const Params& p, int l, int which  , bool from_inputs, bool skip_ctx, int w0, int wstride, int lane) {
;     ...
;   for (; i < nrows; i += wstride) {
;     const int row = rowof(i); const int b = row / TB, s = row % TB;
;     f32x4 v[4];
; #pragma unroll
;     for (int q = 0; q < 4; ++q) v[q] = vn[q];
;     if (i + wstride < nrows) {
;       const int rn = rowof(i + wstride); const float* src = xsrc_row(p, from_inputs, rn / TB, rn % TB);
; #pragma unroll
;       for (int q = 0; q < 4; ++q) vn[q] = *(const f32x4*)(src + q * 256 + lane * 4);
;     }
;     const float* mod = p.MOD + (size_t)(l * 9 + (s < NCTX ? 8 : b)) * 6144 + (which ? 3 * 1024 : 0);
;     f32x4 sh[4], sc[4];
; #pragma unroll
;     for (int q = 0; q < 4; ++q) { sh[q] = *(const f32x4*)(mod + q * 256 + lane * 4); sc[q] = *(const f32x4*)(mod + 1024 + q * 256 + lane * 4); }
;     float ss = 0.f;
; #pragma unroll
;     for (int q = 0; q < 4; ++q) ss += v[q][0] * v[q][0] + v[q][1] * v[q][1] + v[q][2] * v[q][2] + v[q][3] * v[q][3];
;     ss = red64(ss);
;     const float rs = rsqrtf(ss * (1.f / 1024.f) + EPSF);
;     bf16_t* dst = p.HY + (size_t)row * DM;
; #pragma unroll
;     for (int q = 0; q < 4; ++q) {
;       float o[4];
; #pragma unroll
;       for (int j = 0; j < 4; ++j) o[j] = (v[q][j] * rs * gg[q][j]) * (1.f + sc[q][j]) + sh[q][j];
;       u32x2 w = {pk_bf16(o[0], o[1]), pk_bf16(o[2], o[3])};
;       *(u32x2*)(dst + q * 256 + lane * 4) = w;
;     }
	v_pk_mul_f32 v[246:247], v[122:123], v[122:123]
	v_pk_fma_f32 v[246:247], v[124:125], v[124:125], v[246:247]
	v_pk_fma_f32 v[246:247], v[126:127], v[126:127], v[246:247]
	v_pk_fma_f32 v[246:247], v[128:129], v[128:129], v[246:247]
	v_pk_fma_f32 v[246:247], v[130:131], v[130:131], v[246:247]
	v_pk_fma_f32 v[246:247], v[132:133], v[132:133], v[246:247]
	v_pk_fma_f32 v[246:247], v[134:135], v[134:135], v[246:247]
	v_pk_fma_f32 v[246:247], v[136:137], v[136:137], v[246:247]
	s_nop 0
	v_add_f32_e32 v246, v246, v247
	s_nop 1
	v_add_f32_dpp v246, v246, v246 quad_perm:[1,0,3,2] row_mask:0xf bank_mask:0xf
	s_nop 1
	v_add_f32_dpp v246, v246, v246 quad_perm:[2,3,0,1] row_mask:0xf bank_mask:0xf
	s_nop 1
	v_add_f32_dpp v246, v246, v246 row_half_mirror row_mask:0xf bank_mask:0xf
	s_nop 1
	v_add_f32_dpp v246, v246, v246 row_mirror row_mask:0xf bank_mask:0xf
	s_nop 1
	v_add_f32_dpp v246, v246, v246 row_bcast:15 row_mask:0xa bank_mask:0xf
	s_nop 1
	v_add_f32_dpp v246, v246, v246 row_bcast:31 row_mask:0xc bank_mask:0xf
	s_nop 1
	v_readlane_b32 s0, v246, 63
	s_add_i32 s21, s20, 4096
	s_lshl_b32 s21, s21, 11
	s_add_u32 s10, s16, s21
	s_addc_u32 s11, s17, 0
	v_mov_b32_e32 v248, s0
	v_fmamk_f32 v248, v248, 0x3a800000, v143
	v_rsq_f32_e32 v248, v248
	s_nop 0
	v_pk_mul_f32 v[122:123], v[122:123], v[248:249] op_sel_hi:[1,0]
	v_pk_add_f32 v[176:177], v[176:177], 1.0 op_sel_hi:[1,0]
	v_pk_mul_f32 v[122:123], v[2:3], v[122:123]
	v_pk_fma_f32 v[122:123], v[176:177], v[122:123], v[160:161]
	v_pk_mul_f32 v[124:125], v[124:125], v[248:249] op_sel_hi:[1,0]
	v_pk_add_f32 v[178:179], v[178:179], 1.0 op_sel_hi:[1,0]
	v_pk_mul_f32 v[124:125], v[4:5], v[124:125]
	v_pk_fma_f32 v[124:125], v[178:179], v[124:125], v[162:163]
	v_cvt_pk_bf16_f32 v160, v122, v123
	v_cvt_pk_bf16_f32 v161, v124, v125
	global_store_dwordx2 v245, v[160:161], s[10:11]
	v_pk_mul_f32 v[126:127], v[126:127], v[248:249] op_sel_hi:[1,0]
	v_pk_add_f32 v[180:181], v[180:181], 1.0 op_sel_hi:[1,0]
	v_pk_mul_f32 v[126:127], v[6:7], v[126:127]
	v_pk_fma_f32 v[126:127], v[180:181], v[126:127], v[164:165]
	v_pk_mul_f32 v[128:129], v[128:129], v[248:249] op_sel_hi:[1,0]
	v_pk_add_f32 v[182:183], v[182:183], 1.0 op_sel_hi:[1,0]
	v_pk_mul_f32 v[128:129], v[8:9], v[128:129]
	v_pk_fma_f32 v[128:129], v[182:183], v[128:129], v[166:167]
	v_cvt_pk_bf16_f32 v164, v126, v127
	v_cvt_pk_bf16_f32 v165, v128, v129
	global_store_dwordx2 v245, v[164:165], s[10:11] offset:512
	v_pk_mul_f32 v[130:131], v[130:131], v[248:249] op_sel_hi:[1,0]
	v_pk_add_f32 v[184:185], v[184:185], 1.0 op_sel_hi:[1,0]
	v_pk_mul_f32 v[130:131], v[10:11], v[130:131]
	v_pk_fma_f32 v[130:131], v[184:185], v[130:131], v[168:169]
	v_pk_mul_f32 v[132:133], v[132:133], v[248:249] op_sel_hi:[1,0]
	v_pk_add_f32 v[186:187], v[186:187], 1.0 op_sel_hi:[1,0]
	v_pk_mul_f32 v[132:133], v[12:13], v[132:133]
	v_pk_fma_f32 v[132:133], v[186:187], v[132:133], v[170:171]
	v_cvt_pk_bf16_f32 v168, v130, v131
	v_cvt_pk_bf16_f32 v169, v132, v133
	global_store_dwordx2 v245, v[168:169], s[10:11] offset:1024
	v_pk_mul_f32 v[134:135], v[134:135], v[248:249] op_sel_hi:[1,0]
	v_pk_add_f32 v[188:189], v[188:189], 1.0 op_sel_hi:[1,0]
	v_pk_mul_f32 v[134:135], v[14:15], v[134:135]
	v_pk_fma_f32 v[134:135], v[188:189], v[134:135], v[172:173]
	v_pk_mul_f32 v[136:137], v[136:137], v[248:249] op_sel_hi:[1,0]
	v_pk_add_f32 v[190:191], v[190:191], 1.0 op_sel_hi:[1,0]
	v_pk_mul_f32 v[136:137], v[16:17], v[136:137]
	v_pk_fma_f32 v[136:137], v[190:191], v[136:137], v[174:175]
	v_cvt_pk_bf16_f32 v172, v134, v135
	v_cvt_pk_bf16_f32 v173, v136, v137
	global_store_dwordx2 v245, v[172:173], s[10:11] offset:1536
	s_add_i32 s21, s20, 10240
	s_mul_hi_u32 s7, s21, 0x38e38e39
	s_lshr_b32 s7, s7, 9
	s_mul_i32 s8, s7, 0x900
	s_sub_i32 s8, s21, s8
	s_lshl_b32 s9, s7, 11
	s_add_i32 s9, s9, s8
	s_add_i32 s9, s9, 0xffffff00
	s_lshl_b32 s10, s7, 8
	s_add_i32 s10, s10, s8
	s_cmpk_gt_i32 s8, 0xff
	s_cselect_b32 s9, s9, s10
	s_cselect_b32 s26, s12, s14
	s_cselect_b32 s27, s13, s15
	s_cselect_b32 s10, s7, 8
	s_lshl_b32 s9, s9, 12
	s_add_u32 s26, s26, s9
	s_addc_u32 s27, s27, 0
	s_add_i32 s10, s10, s82
	s_mul_i32 s10, s10, s24
	s_add_u32 s28, s58, s10
	s_addc_u32 s29, s59, 0
	s_add_u32 s28, s28, 0x0
	s_addc_u32 s29, s29, 0
	s_add_u32 s0, s28, 0x1000
	s_addc_u32 s1, s29, 0
	global_load_dwordx4 v[122:125], v244, s[26:27]
	global_load_dwordx4 v[126:129], v244, s[26:27] offset:1024
	global_load_dwordx4 v[130:133], v244, s[26:27] offset:2048
	global_load_dwordx4 v[134:137], v244, s[26:27] offset:3072
	global_load_dwordx4 v[160:163], v244, s[28:29]
	global_load_dwordx4 v[164:167], v244, s[28:29] offset:1024
	global_load_dwordx4 v[168:171], v244, s[28:29] offset:2048
	global_load_dwordx4 v[172:175], v244, s[28:29] offset:3072
	global_load_dwordx4 v[176:179], v244, s[0:1]
	global_load_dwordx4 v[180:183], v244, s[0:1] offset:1024
	global_load_dwordx4 v[184:187], v244, s[0:1] offset:2048
	global_load_dwordx4 v[188:191], v244, s[0:1] offset:3072
	s_waitcnt vmcnt(32)
; DI unsigned pk_bf16(float lo, float hi) { f32x2 v = {lo, hi}; bf16v2 b = __builtin_convertvector(v, bf16v2); return __builtin_bit_cast(unsigned, b); }
; DI float red64(float x) { for (int o = 32; o > 0; o >>= 1) x += __shfl_xor(x, o); return x; }
; DI void modnorm_rows(const Params& p, int l, int which  , bool from_inputs, bool skip_ctx, int w0, int wstride, int lane) {
;     ...
;   for (; i < nrows; i += wstride) {
;     const int row = rowof(i); const int b = row / TB, s = row % TB;
;     f32x4 v[4];
; #pragma unroll
;     for (int q = 0; q < 4; ++q) v[q] = vn[q];
;     if (i + wstride < nrows) {
;       const int rn = rowof(i + wstride); const float* src = xsrc_row(p, from_inputs, rn / TB, rn % TB);
; #pragma unroll
;       for (int q = 0; q < 4; ++q) vn[q] = *(const f32x4*)(src + q * 256 + lane * 4);
;     }
;     const float* mod = p.MOD + (size_t)(l * 9 + (s < NCTX ? 8 : b)) * 6144 + (which ? 3 * 1024 : 0);
;     f32x4 sh[4], sc[4];
; #pragma unroll
;     for (int q = 0; q < 4; ++q) { sh[q] = *(const f32x4*)(mod + q * 256 + lane * 4); sc[q] = *(const f32x4*)(mod + 1024 + q * 256 + lane * 4); }
;     float ss = 0.f;
; #pragma unroll
;     for (int q = 0; q < 4; ++q) ss += v[q][0] * v[q][0] + v[q][1] * v[q][1] + v[q][2] * v[q][2] + v[q][3] * v[q][3];
;     ss = red64(ss);
;     const float rs = rsqrtf(ss * (1.f / 1024.f) + EPSF);
;     bf16_t* dst = p.HY + (size_t)row * DM;
; #pragma unroll
;     for (int q = 0; q < 4; ++q) {
;       float o[4];
; #pragma unroll
;       for (int j = 0; j < 4; ++j) o[j] = (v[q][j] * rs * gg[q][j]) * (1.f + sc[q][j]) + sh[q][j];
;       u32x2 w = {pk_bf16(o[0], o[1]), pk_bf16(o[2], o[3])};
;       *(u32x2*)(dst + q * 256 + lane * 4) = w;
;     }
	v_pk_mul_f32 v[246:247], v[18:19], v[18:19]
	v_pk_fma_f32 v[246:247], v[20:21], v[20:21], v[246:247]
	v_pk_fma_f32 v[246:247], v[22:23], v[22:23], v[246:247]
	v_pk_fma_f32 v[246:247], v[24:25], v[24:25], v[246:247]
	v_pk_fma_f32 v[246:247], v[26:27], v[26:27], v[246:247]
	v_pk_fma_f32 v[246:247], v[28:29], v[28:29], v[246:247]
	v_pk_fma_f32 v[246:247], v[30:31], v[30:31], v[246:247]
	v_pk_fma_f32 v[246:247], v[32:33], v[32:33], v[246:247]
	s_nop 0
	v_add_f32_e32 v246, v246, v247
	s_nop 1
	v_add_f32_dpp v246, v246, v246 quad_perm:[1,0,3,2] row_mask:0xf bank_mask:0xf
	s_nop 1
	v_add_f32_dpp v246, v246, v246 quad_perm:[2,3,0,1] row_mask:0xf bank_mask:0xf
	s_nop 1
	v_add_f32_dpp v246, v246, v246 row_half_mirror row_mask:0xf bank_mask:0xf
	s_nop 1
	v_add_f32_dpp v246, v246, v246 row_mirror row_mask:0xf bank_mask:0xf
	s_nop 1
	v_add_f32_dpp v246, v246, v246 row_bcast:15 row_mask:0xa bank_mask:0xf
	s_nop 1
	v_add_f32_dpp v246, v246, v246 row_bcast:31 row_mask:0xc bank_mask:0xf
	s_nop 1
	v_readlane_b32 s0, v246, 63
	s_add_i32 s21, s20, 6144
	s_lshl_b32 s21, s21, 11
	s_add_u32 s10, s16, s21
	s_addc_u32 s11, s17, 0
	v_mov_b32_e32 v248, s0
	v_fmamk_f32 v248, v248, 0x3a800000, v143
	v_rsq_f32_e32 v248, v248
	s_nop 0
	v_pk_mul_f32 v[18:19], v[18:19], v[248:249] op_sel_hi:[1,0]
	v_pk_add_f32 v[50:51], v[50:51], 1.0 op_sel_hi:[1,0]
	v_pk_mul_f32 v[18:19], v[2:3], v[18:19]
	v_pk_fma_f32 v[18:19], v[50:51], v[18:19], v[34:35]
	v_pk_mul_f32 v[20:21], v[20:21], v[248:249] op_sel_hi:[1,0]
	v_pk_add_f32 v[52:53], v[52:53], 1.0 op_sel_hi:[1,0]
	v_pk_mul_f32 v[20:21], v[4:5], v[20:21]
	v_pk_fma_f32 v[20:21], v[52:53], v[20:21], v[36:37]
	v_cvt_pk_bf16_f32 v34, v18, v19
	v_cvt_pk_bf16_f32 v35, v20, v21
	global_store_dwordx2 v245, v[34:35], s[10:11]
	v_pk_mul_f32 v[22:23], v[22:23], v[248:249] op_sel_hi:[1,0]
	v_pk_add_f32 v[54:55], v[54:55], 1.0 op_sel_hi:[1,0]
	v_pk_mul_f32 v[22:23], v[6:7], v[22:23]
	v_pk_fma_f32 v[22:23], v[54:55], v[22:23], v[38:39]
	v_pk_mul_f32 v[24:25], v[24:25], v[248:249] op_sel_hi:[1,0]
	v_pk_add_f32 v[56:57], v[56:57], 1.0 op_sel_hi:[1,0]
	v_pk_mul_f32 v[24:25], v[8:9], v[24:25]
	v_pk_fma_f32 v[24:25], v[56:57], v[24:25], v[40:41]
	v_cvt_pk_bf16_f32 v38, v22, v23
	v_cvt_pk_bf16_f32 v39, v24, v25
	global_store_dwordx2 v245, v[38:39], s[10:11] offset:512
	v_pk_mul_f32 v[26:27], v[26:27], v[248:249] op_sel_hi:[1,0]
	v_pk_add_f32 v[58:59], v[58:59], 1.0 op_sel_hi:[1,0]
	v_pk_mul_f32 v[26:27], v[10:11], v[26:27]
	v_pk_fma_f32 v[26:27], v[58:59], v[26:27], v[42:43]
	v_pk_mul_f32 v[28:29], v[28:29], v[248:249] op_sel_hi:[1,0]
	v_pk_add_f32 v[60:61], v[60:61], 1.0 op_sel_hi:[1,0]
	v_pk_mul_f32 v[28:29], v[12:13], v[28:29]
	v_pk_fma_f32 v[28:29], v[60:61], v[28:29], v[44:45]
	v_cvt_pk_bf16_f32 v42, v26, v27
	v_cvt_pk_bf16_f32 v43, v28, v29
	global_store_dwordx2 v245, v[42:43], s[10:11] offset:1024
	v_pk_mul_f32 v[30:31], v[30:31], v[248:249] op_sel_hi:[1,0]
	v_pk_add_f32 v[62:63], v[62:63], 1.0 op_sel_hi:[1,0]
	v_pk_mul_f32 v[30:31], v[14:15], v[30:31]
	v_pk_fma_f32 v[30:31], v[62:63], v[30:31], v[46:47]
	v_pk_mul_f32 v[32:33], v[32:33], v[248:249] op_sel_hi:[1,0]
	v_pk_add_f32 v[64:65], v[64:65], 1.0 op_sel_hi:[1,0]
	v_pk_mul_f32 v[32:33], v[16:17], v[32:33]
	v_pk_fma_f32 v[32:33], v[64:65], v[32:33], v[48:49]
	v_cvt_pk_bf16_f32 v46, v30, v31
	v_cvt_pk_bf16_f32 v47, v32, v33
	global_store_dwordx2 v245, v[46:47], s[10:11] offset:1536
	s_add_i32 s21, s20, 12288
	s_mul_hi_u32 s7, s21, 0x38e38e39
	s_lshr_b32 s7, s7, 9
	s_mul_i32 s8, s7, 0x900
	s_sub_i32 s8, s21, s8
	s_lshl_b32 s9, s7, 11
	s_add_i32 s9, s9, s8
	s_add_i32 s9, s9, 0xffffff00
	s_lshl_b32 s10, s7, 8
	s_add_i32 s10, s10, s8
	s_cmpk_gt_i32 s8, 0xff
	s_cselect_b32 s9, s9, s10
	s_cselect_b32 s26, s12, s14
	s_cselect_b32 s27, s13, s15
	s_cselect_b32 s10, s7, 8
	s_lshl_b32 s9, s9, 12
	s_add_u32 s26, s26, s9
	s_addc_u32 s27, s27, 0
	s_add_i32 s10, s10, s82
	s_mul_i32 s10, s10, s24
	s_add_u32 s28, s58, s10
	s_addc_u32 s29, s59, 0
	s_add_u32 s28, s28, 0x0
	s_addc_u32 s29, s29, 0
	s_add_u32 s0, s28, 0x1000
	s_addc_u32 s1, s29, 0
	global_load_dwordx4 v[18:21], v244, s[26:27]
	global_load_dwordx4 v[22:25], v244, s[26:27] offset:1024
	global_load_dwordx4 v[26:29], v244, s[26:27] offset:2048
	global_load_dwordx4 v[30:33], v244, s[26:27] offset:3072
	global_load_dwordx4 v[34:37], v244, s[28:29]
	global_load_dwordx4 v[38:41], v244, s[28:29] offset:1024
	global_load_dwordx4 v[42:45], v244, s[28:29] offset:2048
	global_load_dwordx4 v[46:49], v244, s[28:29] offset:3072
	global_load_dwordx4 v[50:53], v244, s[0:1]
	global_load_dwordx4 v[54:57], v244, s[0:1] offset:1024
	global_load_dwordx4 v[58:61], v244, s[0:1] offset:2048
	global_load_dwordx4 v[62:65], v244, s[0:1] offset:3072
	s_waitcnt vmcnt(32)
; DI unsigned pk_bf16(float lo, float hi) { f32x2 v = {lo, hi}; bf16v2 b = __builtin_convertvector(v, bf16v2); return __builtin_bit_cast(unsigned, b); }
; DI float red64(float x) { for (int o = 32; o > 0; o >>= 1) x += __shfl_xor(x, o); return x; }
; DI void modnorm_rows(const Params& p, int l, int which  , bool from_inputs, bool skip_ctx, int w0, int wstride, int lane) {
;     ...
;   for (; i < nrows; i += wstride) {
;     const int row = rowof(i); const int b = row / TB, s = row % TB;
;     f32x4 v[4];
; #pragma unroll
;     for (int q = 0; q < 4; ++q) v[q] = vn[q];
;     if (i + wstride < nrows) {
;       const int rn = rowof(i + wstride); const float* src = xsrc_row(p, from_inputs, rn / TB, rn % TB);
; #pragma unroll
;       for (int q = 0; q < 4; ++q) vn[q] = *(const f32x4*)(src + q * 256 + lane * 4);
;     }
;     const float* mod = p.MOD + (size_t)(l * 9 + (s < NCTX ? 8 : b)) * 6144 + (which ? 3 * 1024 : 0);
;     f32x4 sh[4], sc[4];
; #pragma unroll
;     for (int q = 0; q < 4; ++q) { sh[q] = *(const f32x4*)(mod + q * 256 + lane * 4); sc[q] = *(const f32x4*)(mod + 1024 + q * 256 + lane * 4); }
;     float ss = 0.f;
; #pragma unroll
;     for (int q = 0; q < 4; ++q) ss += v[q][0] * v[q][0] + v[q][1] * v[q][1] + v[q][2] * v[q][2] + v[q][3] * v[q][3];
;     ss = red64(ss);
;     const float rs = rsqrtf(ss * (1.f / 1024.f) + EPSF);
;     bf16_t* dst = p.HY + (size_t)row * DM;
; #pragma unroll
;     for (int q = 0; q < 4; ++q) {
;       float o[4];
; #pragma unroll
;       for (int j = 0; j < 4; ++j) o[j] = (v[q][j] * rs * gg[q][j]) * (1.f + sc[q][j]) + sh[q][j];
;       u32x2 w = {pk_bf16(o[0], o[1]), pk_bf16(o[2], o[3])};
;       *(u32x2*)(dst + q * 256 + lane * 4) = w;
;     }
	v_pk_mul_f32 v[246:247], v[66:67], v[66:67]
	v_pk_fma_f32 v[246:247], v[68:69], v[68:69], v[246:247]
	v_pk_fma_f32 v[246:247], v[70:71], v[70:71], v[246:247]
	v_pk_fma_f32 v[246:247], v[72:73], v[72:73], v[246:247]
	v_pk_fma_f32 v[246:247], v[74:75], v[74:75], v[246:247]
	v_pk_fma_f32 v[246:247], v[76:77], v[76:77], v[246:247]
	v_pk_fma_f32 v[246:247], v[78:79], v[78:79], v[246:247]
	v_pk_fma_f32 v[246:247], v[80:81], v[80:81], v[246:247]
	s_nop 0
	v_add_f32_e32 v246, v246, v247
	s_nop 1
	v_add_f32_dpp v246, v246, v246 quad_perm:[1,0,3,2] row_mask:0xf bank_mask:0xf
	s_nop 1
	v_add_f32_dpp v246, v246, v246 quad_perm:[2,3,0,1] row_mask:0xf bank_mask:0xf
	s_nop 1
	v_add_f32_dpp v246, v246, v246 row_half_mirror row_mask:0xf bank_mask:0xf
	s_nop 1
	v_add_f32_dpp v246, v246, v246 row_mirror row_mask:0xf bank_mask:0xf
	s_nop 1
	v_add_f32_dpp v246, v246, v246 row_bcast:15 row_mask:0xa bank_mask:0xf
	s_nop 1
	v_add_f32_dpp v246, v246, v246 row_bcast:31 row_mask:0xc bank_mask:0xf
	s_nop 1
	v_readlane_b32 s0, v246, 63
	s_add_i32 s21, s20, 8192
	s_lshl_b32 s21, s21, 11
	s_add_u32 s10, s16, s21
	s_addc_u32 s11, s17, 0
	v_mov_b32_e32 v248, s0
	v_fmamk_f32 v248, v248, 0x3a800000, v143
	v_rsq_f32_e32 v248, v248
	s_nop 0
	v_pk_mul_f32 v[66:67], v[66:67], v[248:249] op_sel_hi:[1,0]
	v_pk_add_f32 v[98:99], v[98:99], 1.0 op_sel_hi:[1,0]
	v_pk_mul_f32 v[66:67], v[2:3], v[66:67]
	v_pk_fma_f32 v[66:67], v[98:99], v[66:67], v[82:83]
	v_pk_mul_f32 v[68:69], v[68:69], v[248:249] op_sel_hi:[1,0]
	v_pk_add_f32 v[100:101], v[100:101], 1.0 op_sel_hi:[1,0]
	v_pk_mul_f32 v[68:69], v[4:5], v[68:69]
	v_pk_fma_f32 v[68:69], v[100:101], v[68:69], v[84:85]
	v_cvt_pk_bf16_f32 v82, v66, v67
	v_cvt_pk_bf16_f32 v83, v68, v69
	global_store_dwordx2 v245, v[82:83], s[10:11]
	v_pk_mul_f32 v[70:71], v[70:71], v[248:249] op_sel_hi:[1,0]
	v_pk_add_f32 v[102:103], v[102:103], 1.0 op_sel_hi:[1,0]
	v_pk_mul_f32 v[70:71], v[6:7], v[70:71]
	v_pk_fma_f32 v[70:71], v[102:103], v[70:71], v[86:87]
	v_pk_mul_f32 v[72:73], v[72:73], v[248:249] op_sel_hi:[1,0]
	v_pk_add_f32 v[104:105], v[104:105], 1.0 op_sel_hi:[1,0]
	v_pk_mul_f32 v[72:73], v[8:9], v[72:73]
	v_pk_fma_f32 v[72:73], v[104:105], v[72:73], v[88:89]
	v_cvt_pk_bf16_f32 v86, v70, v71
	v_cvt_pk_bf16_f32 v87, v72, v73
	global_store_dwordx2 v245, v[86:87], s[10:11] offset:512
	v_pk_mul_f32 v[74:75], v[74:75], v[248:249] op_sel_hi:[1,0]
	v_pk_add_f32 v[106:107], v[106:107], 1.0 op_sel_hi:[1,0]
	v_pk_mul_f32 v[74:75], v[10:11], v[74:75]
	v_pk_fma_f32 v[74:75], v[106:107], v[74:75], v[90:91]
	v_pk_mul_f32 v[76:77], v[76:77], v[248:249] op_sel_hi:[1,0]
	v_pk_add_f32 v[108:109], v[108:109], 1.0 op_sel_hi:[1,0]
	v_pk_mul_f32 v[76:77], v[12:13], v[76:77]
	v_pk_fma_f32 v[76:77], v[108:109], v[76:77], v[92:93]
	v_cvt_pk_bf16_f32 v90, v74, v75
	v_cvt_pk_bf16_f32 v91, v76, v77
	global_store_dwordx2 v245, v[90:91], s[10:11] offset:1024
	v_pk_mul_f32 v[78:79], v[78:79], v[248:249] op_sel_hi:[1,0]
	v_pk_add_f32 v[118:119], v[118:119], 1.0 op_sel_hi:[1,0]
	v_pk_mul_f32 v[78:79], v[14:15], v[78:79]
	v_pk_fma_f32 v[78:79], v[118:119], v[78:79], v[94:95]
	v_pk_mul_f32 v[80:81], v[80:81], v[248:249] op_sel_hi:[1,0]
	v_pk_add_f32 v[120:121], v[120:121], 1.0 op_sel_hi:[1,0]
	v_pk_mul_f32 v[80:81], v[16:17], v[80:81]
	v_pk_fma_f32 v[80:81], v[120:121], v[80:81], v[96:97]
	v_cvt_pk_bf16_f32 v94, v78, v79
	v_cvt_pk_bf16_f32 v95, v80, v81
	global_store_dwordx2 v245, v[94:95], s[10:11] offset:1536
	s_add_i32 s21, s20, 14336
	s_mul_hi_u32 s7, s21, 0x38e38e39
	s_lshr_b32 s7, s7, 9
	s_mul_i32 s8, s7, 0x900
	s_sub_i32 s8, s21, s8
	s_lshl_b32 s9, s7, 11
	s_add_i32 s9, s9, s8
	s_add_i32 s9, s9, 0xffffff00
	s_lshl_b32 s10, s7, 8
	s_add_i32 s10, s10, s8
	s_cmpk_gt_i32 s8, 0xff
	s_cselect_b32 s9, s9, s10
	s_cselect_b32 s26, s12, s14
	s_cselect_b32 s27, s13, s15
	s_cselect_b32 s10, s7, 8
	s_lshl_b32 s9, s9, 12
	s_add_u32 s26, s26, s9
	s_addc_u32 s27, s27, 0
	s_add_i32 s10, s10, s82
	s_mul_i32 s10, s10, s24
	s_add_u32 s28, s58, s10
	s_addc_u32 s29, s59, 0
	s_add_u32 s28, s28, 0x0
	s_addc_u32 s29, s29, 0
	s_add_u32 s0, s28, 0x1000
	s_addc_u32 s1, s29, 0
	global_load_dwordx4 v[66:69], v244, s[26:27]
	global_load_dwordx4 v[70:73], v244, s[26:27] offset:1024
	global_load_dwordx4 v[74:77], v244, s[26:27] offset:2048
	global_load_dwordx4 v[78:81], v244, s[26:27] offset:3072
	global_load_dwordx4 v[82:85], v244, s[28:29]
	global_load_dwordx4 v[86:89], v244, s[28:29] offset:1024
	global_load_dwordx4 v[90:93], v244, s[28:29] offset:2048
	global_load_dwordx4 v[94:97], v244, s[28:29] offset:3072
	global_load_dwordx4 v[98:101], v244, s[0:1]
	global_load_dwordx4 v[102:105], v244, s[0:1] offset:1024
	global_load_dwordx4 v[106:109], v244, s[0:1] offset:2048
	global_load_dwordx4 v[118:121], v244, s[0:1] offset:3072
	s_waitcnt vmcnt(32)
; DI unsigned pk_bf16(float lo, float hi) { f32x2 v = {lo, hi}; bf16v2 b = __builtin_convertvector(v, bf16v2); return __builtin_bit_cast(unsigned, b); }
; DI float red64(float x) { for (int o = 32; o > 0; o >>= 1) x += __shfl_xor(x, o); return x; }
; DI void modnorm_rows(const Params& p, int l, int which  , bool from_inputs, bool skip_ctx, int w0, int wstride, int lane) {
;     ...
;   for (; i < nrows; i += wstride) {
;     const int row = rowof(i); const int b = row / TB, s = row % TB;
;     f32x4 v[4];
; #pragma unroll
;     for (int q = 0; q < 4; ++q) v[q] = vn[q];
;     if (i + wstride < nrows) {
;       const int rn = rowof(i + wstride); const float* src = xsrc_row(p, from_inputs, rn / TB, rn % TB);
; #pragma unroll
;       for (int q = 0; q < 4; ++q) vn[q] = *(const f32x4*)(src + q * 256 + lane * 4);
;     }
;     const float* mod = p.MOD + (size_t)(l * 9 + (s < NCTX ? 8 : b)) * 6144 + (which ? 3 * 1024 : 0);
;     f32x4 sh[4], sc[4];
; #pragma unroll
;     for (int q = 0; q < 4; ++q) { sh[q] = *(const f32x4*)(mod + q * 256 + lane * 4); sc[q] = *(const f32x4*)(mod + 1024 + q * 256 + lane * 4); }
;     float ss = 0.f;
; #pragma unroll
;     for (int q = 0; q < 4; ++q) ss += v[q][0] * v[q][0] + v[q][1] * v[q][1] + v[q][2] * v[q][2] + v[q][3] * v[q][3];
;     ss = red64(ss);
;     const float rs = rsqrtf(ss * (1.f / 1024.f) + EPSF);
;     bf16_t* dst = p.HY + (size_t)row * DM;
; #pragma unroll
;     for (int q = 0; q < 4; ++q) {
;       float o[4];
; #pragma unroll
;       for (int j = 0; j < 4; ++j) o[j] = (v[q][j] * rs * gg[q][j]) * (1.f + sc[q][j]) + sh[q][j];
;       u32x2 w = {pk_bf16(o[0], o[1]), pk_bf16(o[2], o[3])};
;       *(u32x2*)(dst + q * 256 + lane * 4) = w;
;     }
	v_pk_mul_f32 v[246:247], v[122:123], v[122:123]
	v_pk_fma_f32 v[246:247], v[124:125], v[124:125], v[246:247]
	v_pk_fma_f32 v[246:247], v[126:127], v[126:127], v[246:247]
	v_pk_fma_f32 v[246:247], v[128:129], v[128:129], v[246:247]
	v_pk_fma_f32 v[246:247], v[130:131], v[130:131], v[246:247]
	v_pk_fma_f32 v[246:247], v[132:133], v[132:133], v[246:247]
	v_pk_fma_f32 v[246:247], v[134:135], v[134:135], v[246:247]
	v_pk_fma_f32 v[246:247], v[136:137], v[136:137], v[246:247]
	s_nop 0
	v_add_f32_e32 v246, v246, v247
	s_nop 1
	v_add_f32_dpp v246, v246, v246 quad_perm:[1,0,3,2] row_mask:0xf bank_mask:0xf
	s_nop 1
	v_add_f32_dpp v246, v246, v246 quad_perm:[2,3,0,1] row_mask:0xf bank_mask:0xf
	s_nop 1
	v_add_f32_dpp v246, v246, v246 row_half_mirror row_mask:0xf bank_mask:0xf
	s_nop 1
	v_add_f32_dpp v246, v246, v246 row_mirror row_mask:0xf bank_mask:0xf
	s_nop 1
	v_add_f32_dpp v246, v246, v246 row_bcast:15 row_mask:0xa bank_mask:0xf
	s_nop 1
	v_add_f32_dpp v246, v246, v246 row_bcast:31 row_mask:0xc bank_mask:0xf
	s_nop 1
	v_readlane_b32 s0, v246, 63
	s_add_i32 s21, s20, 10240
	s_lshl_b32 s21, s21, 11
	s_add_u32 s10, s16, s21
	s_addc_u32 s11, s17, 0
	v_mov_b32_e32 v248, s0
	v_fmamk_f32 v248, v248, 0x3a800000, v143
	v_rsq_f32_e32 v248, v248
	s_nop 0
	v_pk_mul_f32 v[122:123], v[122:123], v[248:249] op_sel_hi:[1,0]
	v_pk_add_f32 v[176:177], v[176:177], 1.0 op_sel_hi:[1,0]
	v_pk_mul_f32 v[122:123], v[2:3], v[122:123]
	v_pk_fma_f32 v[122:123], v[176:177], v[122:123], v[160:161]
	v_pk_mul_f32 v[124:125], v[124:125], v[248:249] op_sel_hi:[1,0]
	v_pk_add_f32 v[178:179], v[178:179], 1.0 op_sel_hi:[1,0]
	v_pk_mul_f32 v[124:125], v[4:5], v[124:125]
	v_pk_fma_f32 v[124:125], v[178:179], v[124:125], v[162:163]
	v_cvt_pk_bf16_f32 v160, v122, v123
	v_cvt_pk_bf16_f32 v161, v124, v125
	global_store_dwordx2 v245, v[160:161], s[10:11]
	v_pk_mul_f32 v[126:127], v[126:127], v[248:249] op_sel_hi:[1,0]
	v_pk_add_f32 v[180:181], v[180:181], 1.0 op_sel_hi:[1,0]
	v_pk_mul_f32 v[126:127], v[6:7], v[126:127]
	v_pk_fma_f32 v[126:127], v[180:181], v[126:127], v[164:165]
	v_pk_mul_f32 v[128:129], v[128:129], v[248:249] op_sel_hi:[1,0]
	v_pk_add_f32 v[182:183], v[182:183], 1.0 op_sel_hi:[1,0]
	v_pk_mul_f32 v[128:129], v[8:9], v[128:129]
	v_pk_fma_f32 v[128:129], v[182:183], v[128:129], v[166:167]
	v_cvt_pk_bf16_f32 v164, v126, v127
	v_cvt_pk_bf16_f32 v165, v128, v129
	global_store_dwordx2 v245, v[164:165], s[10:11] offset:512
	v_pk_mul_f32 v[130:131], v[130:131], v[248:249] op_sel_hi:[1,0]
	v_pk_add_f32 v[184:185], v[184:185], 1.0 op_sel_hi:[1,0]
	v_pk_mul_f32 v[130:131], v[10:11], v[130:131]
	v_pk_fma_f32 v[130:131], v[184:185], v[130:131], v[168:169]
	v_pk_mul_f32 v[132:133], v[132:133], v[248:249] op_sel_hi:[1,0]
	v_pk_add_f32 v[186:187], v[186:187], 1.0 op_sel_hi:[1,0]
	v_pk_mul_f32 v[132:133], v[12:13], v[132:133]
	v_pk_fma_f32 v[132:133], v[186:187], v[132:133], v[170:171]
	v_cvt_pk_bf16_f32 v168, v130, v131
	v_cvt_pk_bf16_f32 v169, v132, v133
	global_store_dwordx2 v245, v[168:169], s[10:11] offset:1024
	v_pk_mul_f32 v[134:135], v[134:135], v[248:249] op_sel_hi:[1,0]
	v_pk_add_f32 v[188:189], v[188:189], 1.0 op_sel_hi:[1,0]
	v_pk_mul_f32 v[134:135], v[14:15], v[134:135]
	v_pk_fma_f32 v[134:135], v[188:189], v[134:135], v[172:173]
	v_pk_mul_f32 v[136:137], v[136:137], v[248:249] op_sel_hi:[1,0]
	v_pk_add_f32 v[190:191], v[190:191], 1.0 op_sel_hi:[1,0]
	v_pk_mul_f32 v[136:137], v[16:17], v[136:137]
	v_pk_fma_f32 v[136:137], v[190:191], v[136:137], v[174:175]
	v_cvt_pk_bf16_f32 v172, v134, v135
	v_cvt_pk_bf16_f32 v173, v136, v137
	global_store_dwordx2 v245, v[172:173], s[10:11] offset:1536
	s_add_i32 s21, s20, 16384
	s_mul_hi_u32 s7, s21, 0x38e38e39
	s_lshr_b32 s7, s7, 9
	s_mul_i32 s8, s7, 0x900
	s_sub_i32 s8, s21, s8
	s_lshl_b32 s9, s7, 11
	s_add_i32 s9, s9, s8
	s_add_i32 s9, s9, 0xffffff00
	s_lshl_b32 s10, s7, 8
	s_add_i32 s10, s10, s8
	s_cmpk_gt_i32 s8, 0xff
	s_cselect_b32 s9, s9, s10
	s_cselect_b32 s26, s12, s14
	s_cselect_b32 s27, s13, s15
	s_cselect_b32 s10, s7, 8
	s_lshl_b32 s9, s9, 12
	s_add_u32 s26, s26, s9
	s_addc_u32 s27, s27, 0
	s_add_i32 s10, s10, s82
	s_mul_i32 s10, s10, s24
	s_add_u32 s28, s58, s10
	s_addc_u32 s29, s59, 0
	s_add_u32 s28, s28, 0x0
	s_addc_u32 s29, s29, 0
	s_add_u32 s0, s28, 0x1000
	s_addc_u32 s1, s29, 0
	global_load_dwordx4 v[122:125], v244, s[26:27]
	global_load_dwordx4 v[126:129], v244, s[26:27] offset:1024
	global_load_dwordx4 v[130:133], v244, s[26:27] offset:2048
	global_load_dwordx4 v[134:137], v244, s[26:27] offset:3072
	global_load_dwordx4 v[160:163], v244, s[28:29]
	global_load_dwordx4 v[164:167], v244, s[28:29] offset:1024
	global_load_dwordx4 v[168:171], v244, s[28:29] offset:2048
	global_load_dwordx4 v[172:175], v244, s[28:29] offset:3072
	global_load_dwordx4 v[176:179], v244, s[0:1]
	global_load_dwordx4 v[180:183], v244, s[0:1] offset:1024
	global_load_dwordx4 v[184:187], v244, s[0:1] offset:2048
	global_load_dwordx4 v[188:191], v244, s[0:1] offset:3072
	s_waitcnt vmcnt(32)
; DI unsigned pk_bf16(float lo, float hi) { f32x2 v = {lo, hi}; bf16v2 b = __builtin_convertvector(v, bf16v2); return __builtin_bit_cast(unsigned, b); }
; DI float red64(float x) { for (int o = 32; o > 0; o >>= 1) x += __shfl_xor(x, o); return x; }
; DI void modnorm_rows(const Params& p, int l, int which  , bool from_inputs, bool skip_ctx, int w0, int wstride, int lane) {
;     ...
;     float ss = 0.f;
; #pragma unroll
;     for (int q = 0; q < 4; ++q) ss += v[q][0] * v[q][0] + v[q][1] * v[q][1] + v[q][2] * v[q][2] + v[q][3] * v[q][3];
;     ss = red64(ss);
;     const float rs = rsqrtf(ss * (1.f / 1024.f) + EPSF);
;     bf16_t* dst = p.HY + (size_t)row * DM;
; #pragma unroll
;     for (int q = 0; q < 4; ++q) {
;       float o[4];
; #pragma unroll
;       for (int j = 0; j < 4; ++j) o[j] = (v[q][j] * rs * gg[q][j]) * (1.f + sc[q][j]) + sh[q][j];
;       u32x2 w = {pk_bf16(o[0], o[1]), pk_bf16(o[2], o[3])};
;       *(u32x2*)(dst + q * 256 + lane * 4) = w;
;     }
	v_pk_mul_f32 v[246:247], v[18:19], v[18:19]
	v_pk_fma_f32 v[246:247], v[20:21], v[20:21], v[246:247]
	v_pk_fma_f32 v[246:247], v[22:23], v[22:23], v[246:247]
	v_pk_fma_f32 v[246:247], v[24:25], v[24:25], v[246:247]
	v_pk_fma_f32 v[246:247], v[26:27], v[26:27], v[246:247]
	v_pk_fma_f32 v[246:247], v[28:29], v[28:29], v[246:247]
	v_pk_fma_f32 v[246:247], v[30:31], v[30:31], v[246:247]
	v_pk_fma_f32 v[246:247], v[32:33], v[32:33], v[246:247]
	s_nop 0
	v_add_f32_e32 v246, v246, v247
	s_nop 1
	v_add_f32_dpp v246, v246, v246 quad_perm:[1,0,3,2] row_mask:0xf bank_mask:0xf
	s_nop 1
	v_add_f32_dpp v246, v246, v246 quad_perm:[2,3,0,1] row_mask:0xf bank_mask:0xf
	s_nop 1
	v_add_f32_dpp v246, v246, v246 row_half_mirror row_mask:0xf bank_mask:0xf
	s_nop 1
	v_add_f32_dpp v246, v246, v246 row_mirror row_mask:0xf bank_mask:0xf
	s_nop 1
	v_add_f32_dpp v246, v246, v246 row_bcast:15 row_mask:0xa bank_mask:0xf
	s_nop 1
	v_add_f32_dpp v246, v246, v246 row_bcast:31 row_mask:0xc bank_mask:0xf
	s_nop 1
	v_readlane_b32 s0, v246, 63
	s_add_i32 s21, s20, 12288
	s_lshl_b32 s21, s21, 11
	s_add_u32 s10, s16, s21
	s_addc_u32 s11, s17, 0
	v_mov_b32_e32 v248, s0
	v_fmamk_f32 v248, v248, 0x3a800000, v143
	v_rsq_f32_e32 v248, v248
	s_nop 0
	v_pk_mul_f32 v[18:19], v[18:19], v[248:249] op_sel_hi:[1,0]
	v_pk_add_f32 v[50:51], v[50:51], 1.0 op_sel_hi:[1,0]
	v_pk_mul_f32 v[18:19], v[2:3], v[18:19]
	v_pk_fma_f32 v[18:19], v[50:51], v[18:19], v[34:35]
	v_pk_mul_f32 v[20:21], v[20:21], v[248:249] op_sel_hi:[1,0]
	v_pk_add_f32 v[52:53], v[52:53], 1.0 op_sel_hi:[1,0]
	v_pk_mul_f32 v[20:21], v[4:5], v[20:21]
	v_pk_fma_f32 v[20:21], v[52:53], v[20:21], v[36:37]
	v_cvt_pk_bf16_f32 v34, v18, v19
	v_cvt_pk_bf16_f32 v35, v20, v21
	global_store_dwordx2 v245, v[34:35], s[10:11]
	v_pk_mul_f32 v[22:23], v[22:23], v[248:249] op_sel_hi:[1,0]
	v_pk_add_f32 v[54:55], v[54:55], 1.0 op_sel_hi:[1,0]
	v_pk_mul_f32 v[22:23], v[6:7], v[22:23]
	v_pk_fma_f32 v[22:23], v[54:55], v[22:23], v[38:39]
	v_pk_mul_f32 v[24:25], v[24:25], v[248:249] op_sel_hi:[1,0]
	v_pk_add_f32 v[56:57], v[56:57], 1.0 op_sel_hi:[1,0]
	v_pk_mul_f32 v[24:25], v[8:9], v[24:25]
	v_pk_fma_f32 v[24:25], v[56:57], v[24:25], v[40:41]
	v_cvt_pk_bf16_f32 v38, v22, v23
	v_cvt_pk_bf16_f32 v39, v24, v25
	global_store_dwordx2 v245, v[38:39], s[10:11] offset:512
	v_pk_mul_f32 v[26:27], v[26:27], v[248:249] op_sel_hi:[1,0]
	v_pk_add_f32 v[58:59], v[58:59], 1.0 op_sel_hi:[1,0]
	v_pk_mul_f32 v[26:27], v[10:11], v[26:27]
	v_pk_fma_f32 v[26:27], v[58:59], v[26:27], v[42:43]
	v_pk_mul_f32 v[28:29], v[28:29], v[248:249] op_sel_hi:[1,0]
	v_pk_add_f32 v[60:61], v[60:61], 1.0 op_sel_hi:[1,0]
	v_pk_mul_f32 v[28:29], v[12:13], v[28:29]
	v_pk_fma_f32 v[28:29], v[60:61], v[28:29], v[44:45]
	v_cvt_pk_bf16_f32 v42, v26, v27
	v_cvt_pk_bf16_f32 v43, v28, v29
	global_store_dwordx2 v245, v[42:43], s[10:11] offset:1024
	v_pk_mul_f32 v[30:31], v[30:31], v[248:249] op_sel_hi:[1,0]
	v_pk_add_f32 v[62:63], v[62:63], 1.0 op_sel_hi:[1,0]
	v_pk_mul_f32 v[30:31], v[14:15], v[30:31]
	v_pk_fma_f32 v[30:31], v[62:63], v[30:31], v[46:47]
	v_pk_mul_f32 v[32:33], v[32:33], v[248:249] op_sel_hi:[1,0]
	v_pk_add_f32 v[64:65], v[64:65], 1.0 op_sel_hi:[1,0]
	v_pk_mul_f32 v[32:33], v[16:17], v[32:33]
	v_pk_fma_f32 v[32:33], v[64:65], v[32:33], v[48:49]
	v_cvt_pk_bf16_f32 v46, v30, v31
	v_cvt_pk_bf16_f32 v47, v32, v33
	global_store_dwordx2 v245, v[46:47], s[10:11] offset:1536
	s_waitcnt vmcnt(20)
	v_pk_mul_f32 v[246:247], v[66:67], v[66:67]
	v_pk_fma_f32 v[246:247], v[68:69], v[68:69], v[246:247]
	v_pk_fma_f32 v[246:247], v[70:71], v[70:71], v[246:247]
	v_pk_fma_f32 v[246:247], v[72:73], v[72:73], v[246:247]
	v_pk_fma_f32 v[246:247], v[74:75], v[74:75], v[246:247]
	v_pk_fma_f32 v[246:247], v[76:77], v[76:77], v[246:247]
	v_pk_fma_f32 v[246:247], v[78:79], v[78:79], v[246:247]
	v_pk_fma_f32 v[246:247], v[80:81], v[80:81], v[246:247]
	s_nop 0
	v_add_f32_e32 v246, v246, v247
	s_nop 1
	v_add_f32_dpp v246, v246, v246 quad_perm:[1,0,3,2] row_mask:0xf bank_mask:0xf
	s_nop 1
	v_add_f32_dpp v246, v246, v246 quad_perm:[2,3,0,1] row_mask:0xf bank_mask:0xf
	s_nop 1
	v_add_f32_dpp v246, v246, v246 row_half_mirror row_mask:0xf bank_mask:0xf
	s_nop 1
	v_add_f32_dpp v246, v246, v246 row_mirror row_mask:0xf bank_mask:0xf
	s_nop 1
	v_add_f32_dpp v246, v246, v246 row_bcast:15 row_mask:0xa bank_mask:0xf
	s_nop 1
	v_add_f32_dpp v246, v246, v246 row_bcast:31 row_mask:0xc bank_mask:0xf
	s_nop 1
	v_readlane_b32 s0, v246, 63
	s_add_i32 s21, s20, 14336
	s_lshl_b32 s21, s21, 11
	s_add_u32 s10, s16, s21
	s_addc_u32 s11, s17, 0
	v_mov_b32_e32 v248, s0
	v_fmamk_f32 v248, v248, 0x3a800000, v143
	v_rsq_f32_e32 v248, v248
	s_nop 0
	v_pk_mul_f32 v[66:67], v[66:67], v[248:249] op_sel_hi:[1,0]
	v_pk_add_f32 v[98:99], v[98:99], 1.0 op_sel_hi:[1,0]
	v_pk_mul_f32 v[66:67], v[2:3], v[66:67]
	v_pk_fma_f32 v[66:67], v[98:99], v[66:67], v[82:83]
	v_pk_mul_f32 v[68:69], v[68:69], v[248:249] op_sel_hi:[1,0]
	v_pk_add_f32 v[100:101], v[100:101], 1.0 op_sel_hi:[1,0]
	v_pk_mul_f32 v[68:69], v[4:5], v[68:69]
	v_pk_fma_f32 v[68:69], v[100:101], v[68:69], v[84:85]
	v_cvt_pk_bf16_f32 v82, v66, v67
	v_cvt_pk_bf16_f32 v83, v68, v69
	global_store_dwordx2 v245, v[82:83], s[10:11]
	v_pk_mul_f32 v[70:71], v[70:71], v[248:249] op_sel_hi:[1,0]
	v_pk_add_f32 v[102:103], v[102:103], 1.0 op_sel_hi:[1,0]
	v_pk_mul_f32 v[70:71], v[6:7], v[70:71]
	v_pk_fma_f32 v[70:71], v[102:103], v[70:71], v[86:87]
	v_pk_mul_f32 v[72:73], v[72:73], v[248:249] op_sel_hi:[1,0]
	v_pk_add_f32 v[104:105], v[104:105], 1.0 op_sel_hi:[1,0]
	v_pk_mul_f32 v[72:73], v[8:9], v[72:73]
	v_pk_fma_f32 v[72:73], v[104:105], v[72:73], v[88:89]
	v_cvt_pk_bf16_f32 v86, v70, v71
	v_cvt_pk_bf16_f32 v87, v72, v73
	global_store_dwordx2 v245, v[86:87], s[10:11] offset:512
	v_pk_mul_f32 v[74:75], v[74:75], v[248:249] op_sel_hi:[1,0]
	v_pk_add_f32 v[106:107], v[106:107], 1.0 op_sel_hi:[1,0]
	v_pk_mul_f32 v[74:75], v[10:11], v[74:75]
	v_pk_fma_f32 v[74:75], v[106:107], v[74:75], v[90:91]
	v_pk_mul_f32 v[76:77], v[76:77], v[248:249] op_sel_hi:[1,0]
	v_pk_add_f32 v[108:109], v[108:109], 1.0 op_sel_hi:[1,0]
	v_pk_mul_f32 v[76:77], v[12:13], v[76:77]
	v_pk_fma_f32 v[76:77], v[108:109], v[76:77], v[92:93]
	v_cvt_pk_bf16_f32 v90, v74, v75
	v_cvt_pk_bf16_f32 v91, v76, v77
	global_store_dwordx2 v245, v[90:91], s[10:11] offset:1024
	v_pk_mul_f32 v[78:79], v[78:79], v[248:249] op_sel_hi:[1,0]
	v_pk_add_f32 v[118:119], v[118:119], 1.0 op_sel_hi:[1,0]
	v_pk_mul_f32 v[78:79], v[14:15], v[78:79]
	v_pk_fma_f32 v[78:79], v[118:119], v[78:79], v[94:95]
	v_pk_mul_f32 v[80:81], v[80:81], v[248:249] op_sel_hi:[1,0]
	v_pk_add_f32 v[120:121], v[120:121], 1.0 op_sel_hi:[1,0]
	v_pk_mul_f32 v[80:81], v[16:17], v[80:81]
	v_pk_fma_f32 v[80:81], v[120:121], v[80:81], v[96:97]
	v_cvt_pk_bf16_f32 v94, v78, v79
	v_cvt_pk_bf16_f32 v95, v80, v81
	global_store_dwordx2 v245, v[94:95], s[10:11] offset:1536
	s_waitcnt vmcnt(8)
; DI unsigned pk_bf16(float lo, float hi) { f32x2 v = {lo, hi}; bf16v2 b = __builtin_convertvector(v, bf16v2); return __builtin_bit_cast(unsigned, b); }
; DI float red64(float x) { for (int o = 32; o > 0; o >>= 1) x += __shfl_xor(x, o); return x; }
; DI void modnorm_rows(const Params& p, int l, int which  , bool from_inputs, bool skip_ctx, int w0, int wstride, int lane) {
;     ...
;     float ss = 0.f;
; #pragma unroll
;     for (int q = 0; q < 4; ++q) ss += v[q][0] * v[q][0] + v[q][1] * v[q][1] + v[q][2] * v[q][2] + v[q][3] * v[q][3];
;     ss = red64(ss);
;     const float rs = rsqrtf(ss * (1.f / 1024.f) + EPSF);
;     bf16_t* dst = p.HY + (size_t)row * DM;
; #pragma unroll
;     for (int q = 0; q < 4; ++q) {
;       float o[4];
; #pragma unroll
;       for (int j = 0; j < 4; ++j) o[j] = (v[q][j] * rs * gg[q][j]) * (1.f + sc[q][j]) + sh[q][j];
;       u32x2 w = {pk_bf16(o[0], o[1]), pk_bf16(o[2], o[3])};
;       *(u32x2*)(dst + q * 256 + lane * 4) = w;
;     }
	v_pk_mul_f32 v[246:247], v[122:123], v[122:123]
	v_pk_fma_f32 v[246:247], v[124:125], v[124:125], v[246:247]
	v_pk_fma_f32 v[246:247], v[126:127], v[126:127], v[246:247]
	v_pk_fma_f32 v[246:247], v[128:129], v[128:129], v[246:247]
	v_pk_fma_f32 v[246:247], v[130:131], v[130:131], v[246:247]
	v_pk_fma_f32 v[246:247], v[132:133], v[132:133], v[246:247]
	v_pk_fma_f32 v[246:247], v[134:135], v[134:135], v[246:247]
	v_pk_fma_f32 v[246:247], v[136:137], v[136:137], v[246:247]
	s_nop 0
	v_add_f32_e32 v246, v246, v247
	s_nop 1
	v_add_f32_dpp v246, v246, v246 quad_perm:[1,0,3,2] row_mask:0xf bank_mask:0xf
	s_nop 1
	v_add_f32_dpp v246, v246, v246 quad_perm:[2,3,0,1] row_mask:0xf bank_mask:0xf
	s_nop 1
	v_add_f32_dpp v246, v246, v246 row_half_mirror row_mask:0xf bank_mask:0xf
	s_nop 1
	v_add_f32_dpp v246, v246, v246 row_mirror row_mask:0xf bank_mask:0xf
	s_nop 1
	v_add_f32_dpp v246, v246, v246 row_bcast:15 row_mask:0xa bank_mask:0xf
	s_nop 1
	v_add_f32_dpp v246, v246, v246 row_bcast:31 row_mask:0xc bank_mask:0xf
	s_nop 1
	v_readlane_b32 s0, v246, 63
	s_add_i32 s21, s20, 16384
	s_lshl_b32 s21, s21, 11
	s_add_u32 s10, s16, s21
	s_addc_u32 s11, s17, 0
	v_mov_b32_e32 v248, s0
	v_fmamk_f32 v248, v248, 0x3a800000, v143
	v_rsq_f32_e32 v248, v248
	s_nop 0
	v_pk_mul_f32 v[122:123], v[122:123], v[248:249] op_sel_hi:[1,0]
	v_pk_add_f32 v[176:177], v[176:177], 1.0 op_sel_hi:[1,0]
	v_pk_mul_f32 v[122:123], v[2:3], v[122:123]
	v_pk_fma_f32 v[122:123], v[176:177], v[122:123], v[160:161]
	v_pk_mul_f32 v[124:125], v[124:125], v[248:249] op_sel_hi:[1,0]
	v_pk_add_f32 v[178:179], v[178:179], 1.0 op_sel_hi:[1,0]
	v_pk_mul_f32 v[124:125], v[4:5], v[124:125]
	v_pk_fma_f32 v[124:125], v[178:179], v[124:125], v[162:163]
	v_cvt_pk_bf16_f32 v160, v122, v123
	v_cvt_pk_bf16_f32 v161, v124, v125
	global_store_dwordx2 v245, v[160:161], s[10:11]
	v_pk_mul_f32 v[126:127], v[126:127], v[248:249] op_sel_hi:[1,0]
	v_pk_add_f32 v[180:181], v[180:181], 1.0 op_sel_hi:[1,0]
	v_pk_mul_f32 v[126:127], v[6:7], v[126:127]
	v_pk_fma_f32 v[126:127], v[180:181], v[126:127], v[164:165]
	v_pk_mul_f32 v[128:129], v[128:129], v[248:249] op_sel_hi:[1,0]
	v_pk_add_f32 v[182:183], v[182:183], 1.0 op_sel_hi:[1,0]
	v_pk_mul_f32 v[128:129], v[8:9], v[128:129]
	v_pk_fma_f32 v[128:129], v[182:183], v[128:129], v[166:167]
	v_cvt_pk_bf16_f32 v164, v126, v127
	v_cvt_pk_bf16_f32 v165, v128, v129
	global_store_dwordx2 v245, v[164:165], s[10:11] offset:512
	v_pk_mul_f32 v[130:131], v[130:131], v[248:249] op_sel_hi:[1,0]
	v_pk_add_f32 v[184:185], v[184:185], 1.0 op_sel_hi:[1,0]
	v_pk_mul_f32 v[130:131], v[10:11], v[130:131]
	v_pk_fma_f32 v[130:131], v[184:185], v[130:131], v[168:169]
	v_pk_mul_f32 v[132:133], v[132:133], v[248:249] op_sel_hi:[1,0]
	v_pk_add_f32 v[186:187], v[186:187], 1.0 op_sel_hi:[1,0]
	v_pk_mul_f32 v[132:133], v[12:13], v[132:133]
	v_pk_fma_f32 v[132:133], v[186:187], v[132:133], v[170:171]
	v_cvt_pk_bf16_f32 v168, v130, v131
	v_cvt_pk_bf16_f32 v169, v132, v133
	global_store_dwordx2 v245, v[168:169], s[10:11] offset:1024
	v_pk_mul_f32 v[134:135], v[134:135], v[248:249] op_sel_hi:[1,0]
	v_pk_add_f32 v[188:189], v[188:189], 1.0 op_sel_hi:[1,0]
	v_pk_mul_f32 v[134:135], v[14:15], v[134:135]
	v_pk_fma_f32 v[134:135], v[188:189], v[134:135], v[172:173]
	v_pk_mul_f32 v[136:137], v[136:137], v[248:249] op_sel_hi:[1,0]
	v_pk_add_f32 v[190:191], v[190:191], 1.0 op_sel_hi:[1,0]
	v_pk_mul_f32 v[136:137], v[16:17], v[136:137]
	v_pk_fma_f32 v[136:137], v[190:191], v[136:137], v[174:175]
	v_cvt_pk_bf16_f32 v172, v134, v135
	v_cvt_pk_bf16_f32 v173, v136, v137
	global_store_dwordx2 v245, v[172:173], s[10:11] offset:1536
	s_branch .Lnorm1_done
